# k21 plus the same loop-edge rotation in the two LayerNorm-fused GEMM K-loops (all 5 live GEMM loops rotated)
# baseline (speedup 1.0000x reference)
;     __device__ bool next(int i, Unit& u) const { if (i >= 2) return false; const int x = c & 7, j = c >> 3; u.pm = 32 * i + 4 * x + (j & 3); u.pn = j >> 2; return true; }
; #define PG8_STAGE(bufoff, gbase, voff) do { _Pragma("unroll") for (int _i = 0; _i < 2; ++_i) \
;         __builtin_amdgcn_global_load_lds((const unsigned*)((const char*)(gbase) + (voff)[_i]), (LAS unsigned*)(lds + (bufoff) + ldsw + _i * 8192), 16, 0, 0); } while (0)
; #define PG8_LDA(dst, b, h) do { _Pragma("unroll") for (int m = 0; m < 4; ++m) _Pragma("unroll") for (int k = 0; k < 2; ++k) dst[m][k] = *(const LAS bf16x8*)(lds + PG8_SA(b, h) + aoff + m * 2048 + k * 1024); } while (0)
; #define PG8_LDB(dst, b, h) do { _Pragma("unroll") for (int n = 0; n < 2; ++n) _Pragma("unroll") for (int k = 0; k < 2; ++k) dst[n][k] = *(const LAS bf16x8*)(lds + PG8_SB(b, h) + boff + n * 2048 + k * 1024); } while (0)
; #define PG8_WAIT_V(n) asm volatile("s_waitcnt vmcnt(" #n ")" ::: "memory")
; #define PG8_WAIT_L(n) asm volatile("s_waitcnt lgkmcnt(" #n ")" ::: "memory")
; #define PG8_BAR __builtin_amdgcn_s_barrier()
; #define PG8_SCHED __builtin_amdgcn_sched_barrier(0)
; template <class Epi, class Sched, bool ALIGN_EPI = true>
; __device__ __forceinline__ void gemm_phase(LAS unsigned char* lds, const Gemm g, const Sched& S, const Epi& E) {
;     ...
;         const bool has_next = S.next(ui + 1, nxt);
;         const char* nA = has_next ? (const char*)g.A + ((size_t)nxt.pm * BM * g.lda + (size_t)nxt.pn * g.a_pn_off) * 2 : cA; const char* nB = has_next ? (const char*)g.Bt + (size_t)nxt.pn * BM * g.ldb * 2 : cB;
;         for (int t = 0; t < nt; t += 2) {
;             const bool last = (t == nt - 2);
;             const char* a1 = cA + (size_t)(t + 1) * kstep;
;             const char* a2 = last ? nA : cA + (size_t)(t + 2) * kstep; const char* b2 = last ? nB : cB + (size_t)(t + 2) * kstep;
;             const char* a3 = a2 + kstep; const char* b3 = b2 + kstep;
;             PG8_LDB(B0, 0, 0); PG8_LDB(B1, 0, 1); PG8_SCHED; PG8_LDA(At, 0, 0); PG8_STAGE(PG8_SA(1, 1), a1 + hA, voffA);
;             PG8_WAIT_V(8); PG8_WAIT_L(0); PG8_BAR; PG8_MMA(0, 0, At, B0); PG8_MMA(0, 1, At, B1); PG8_BAR; PG8_SCHED;
;             PG8_LDA(At, 0, 1); PG8_STAGE(PG8_SB(0, 0), b2, voffB); PG8_STAGE(PG8_SB(0, 1), b2 + hB, voffB); PG8_STAGE(PG8_SA(0, 0), a2, voffA);
.LBB0_666:
	s_mov_b32 s82, s81
	s_or_b32 s81, s17, s68
	s_mov_b64 s[10:11], s[12:13]
	s_lshl_b32 s12, s81, 20
	s_add_u32 s12, s28, s12
	s_addc_u32 s13, s29, 0
	s_and_b64 s[16:17], s[38:39], exec
	s_cselect_b32 s16, s13, s11
	s_cselect_b32 s17, s12, s10
	s_add_u32 s18, s10, 0x100
	s_addc_u32 s19, s11, 0
	s_add_u32 s10, s10, 0x80080
	s_addc_u32 s11, s11, 0
	v_lshl_add_u64 v[132:133], s[10:11], 0, v[166:167]
	v_lshl_add_u64 v[134:135], s[10:11], 0, v[168:169]
	s_mov_b32 s24, -2
	s_mov_b64 s[10:11], 0
	s_add_u32 vcc_lo, s10, 0x100
	s_addc_u32 vcc_hi, s11, 0
	s_add_u32 s25, s18, s10
	s_addc_u32 s26, s19, s11
	s_add_i32 s27, 0, 0x10000
	s_cmp_eq_u32 s24, 28
	s_cselect_b32 s65, s16, s26
	s_cselect_b32 s26, 0, vcc_lo
	s_cselect_b32 s64, s17, s25
	s_cselect_b32 s25, 0, vcc_hi
	s_add_u32 s62, s14, s26
	v_add_u32_e32 v160, s27, v186
	s_addc_u32 s63, s15, s25
	s_add_i32 s25, 0, 0x14000
	ds_read_b128 v[136:139], v160
	ds_read_b128 v[140:143], v160 offset:1024
	ds_read_b128 v[144:147], v160 offset:2048
	ds_read_b128 v[170:173], v160 offset:3072
	v_add_u32_e32 v160, s25, v186
	ds_read_b128 v[174:177], v160
	ds_read_b128 v[178:181], v160 offset:1024
	ds_read_b128 v[182:185], v160 offset:2048
	ds_read_b128 v[208:211], v160 offset:3072
	v_lshl_add_u64 v[244:245], v[132:133], 0, s[10:11]
	s_add_i32 m0, s53, 0xc000
	ds_read_b128 v[212:215], v197
	ds_read_b128 v[216:219], v197 offset:1024
	ds_read_b128 v[220:223], v197 offset:2048
	ds_read_b128 v[224:227], v197 offset:3072
	ds_read_b128 v[228:231], v197 offset:4096
	ds_read_b128 v[232:235], v197 offset:5120
	ds_read_b128 v[236:239], v197 offset:6144
	ds_read_b128 v[240:243], v197 offset:7168
	global_load_lds_dwordx4 v[244:245], off
	v_lshl_add_u64 v[244:245], v[134:135], 0, s[10:11]
	s_add_i32 m0, s53, 0xe000
	s_nop 0
	global_load_lds_dwordx4 v[244:245], off
	s_waitcnt vmcnt(8)
	s_waitcnt lgkmcnt(0)
	s_barrier
	s_setprio 1
	s_waitcnt lgkmcnt(0)
	v_mfma_f32_16x16x32_bf16 v[36:39], v[136:139], v[212:215], 0
	v_mfma_f32_16x16x32_bf16 v[36:39], v[140:143], v[216:219], v[36:39]
	v_mfma_f32_16x16x32_bf16 v[40:43], v[144:147], v[212:215], 0
	v_mfma_f32_16x16x32_bf16 v[40:43], v[170:173], v[216:219], v[40:43]
	v_mfma_f32_16x16x32_bf16 v[68:71], v[136:139], v[220:223], 0
	v_mfma_f32_16x16x32_bf16 v[68:71], v[140:143], v[224:227], v[68:71]
	v_mfma_f32_16x16x32_bf16 v[72:75], v[144:147], v[220:223], 0
	v_mfma_f32_16x16x32_bf16 v[72:75], v[170:173], v[224:227], v[72:75]
	v_mfma_f32_16x16x32_bf16 v[100:103], v[136:139], v[228:231], 0
	v_mfma_f32_16x16x32_bf16 v[100:103], v[140:143], v[232:235], v[100:103]
	v_mfma_f32_16x16x32_bf16 v[104:107], v[144:147], v[228:231], 0
	v_mfma_f32_16x16x32_bf16 v[104:107], v[170:173], v[232:235], v[104:107]
	v_mfma_f32_16x16x32_bf16 v[128:131], v[136:139], v[236:239], 0
	v_mfma_f32_16x16x32_bf16 v[128:131], v[140:143], v[240:243], v[128:131]
	v_mfma_f32_16x16x32_bf16 v[124:127], v[144:147], v[236:239], 0
	v_mfma_f32_16x16x32_bf16 v[124:127], v[170:173], v[240:243], v[124:127]
	s_setprio 0
	s_setprio 1
	v_mfma_f32_16x16x32_bf16 v[8:11], v[174:177], v[212:215], 0
	v_mfma_f32_16x16x32_bf16 v[8:11], v[178:181], v[216:219], v[8:11]
	v_mfma_f32_16x16x32_bf16 v[4:7], v[182:185], v[212:215], 0
	v_mfma_f32_16x16x32_bf16 v[4:7], v[208:211], v[216:219], v[4:7]
	v_mfma_f32_16x16x32_bf16 v[32:35], v[174:177], v[220:223], 0
	v_mfma_f32_16x16x32_bf16 v[32:35], v[178:181], v[224:227], v[32:35]
	v_mfma_f32_16x16x32_bf16 v[28:31], v[182:185], v[220:223], 0
	v_mfma_f32_16x16x32_bf16 v[28:31], v[208:211], v[224:227], v[28:31]
	v_mfma_f32_16x16x32_bf16 v[56:59], v[174:177], v[228:231], 0
	v_mfma_f32_16x16x32_bf16 v[56:59], v[178:181], v[232:235], v[56:59]
	v_mfma_f32_16x16x32_bf16 v[52:55], v[182:185], v[228:231], 0
	v_mfma_f32_16x16x32_bf16 v[52:55], v[208:211], v[232:235], v[52:55]
	v_mfma_f32_16x16x32_bf16 v[80:83], v[174:177], v[236:239], 0
	v_mfma_f32_16x16x32_bf16 v[80:83], v[178:181], v[240:243], v[80:83]
	s_setprio 2
	s_barrier
	v_mfma_f32_16x16x32_bf16 v[76:79], v[182:185], v[236:239], 0
	v_mfma_f32_16x16x32_bf16 v[76:79], v[208:211], v[240:243], v[76:79]
	s_setprio 0
	s_add_i32 s10, s27, s67
	v_lshl_add_u64 v[244:245], s[62:63], 0, v[2:3]
	s_mov_b32 m0, s10
	ds_read_b128 v[212:215], v197 offset:16384
	ds_read_b128 v[216:219], v197 offset:17408
	ds_read_b128 v[220:223], v197 offset:18432
	ds_read_b128 v[224:227], v197 offset:19456
	ds_read_b128 v[228:231], v197 offset:20480
	ds_read_b128 v[232:235], v197 offset:21504
	ds_read_b128 v[236:239], v197 offset:22528
	ds_read_b128 v[240:243], v197 offset:23552
	global_load_lds_dwordx4 v[244:245], off
	s_add_i32 m0, s10, 0x2000
	s_add_u32 s10, s62, 0x80000
	v_lshl_add_u64 v[246:247], s[62:63], 0, v[150:151]
	s_addc_u32 s11, s63, 0
	s_add_i32 s25, s25, s67
	global_load_lds_dwordx4 v[246:247], off
	v_lshl_add_u64 v[248:249], s[10:11], 0, v[2:3]
	s_mov_b32 m0, s25
	v_lshl_add_u64 v[160:161], s[64:65], 0, v[148:149]
	global_load_lds_dwordx4 v[248:249], off
	v_lshl_add_u64 v[248:249], s[10:11], 0, v[150:151]
	s_add_i32 m0, s25, 0x2000
	s_nop 0
	global_load_lds_dwordx4 v[248:249], off
	v_lshl_add_u64 v[248:249], s[64:65], 0, v[0:1]
	s_mov_b32 m0, s53
	s_nop 0
	global_load_lds_dwordx4 v[248:249], off
	s_mov_b32 m0, s66
	s_nop 0
	global_load_lds_dwordx4 v[160:161], off
	s_waitcnt vmcnt(8)
	s_waitcnt lgkmcnt(0)
	s_barrier
; #define PG8_STAGE(bufoff, gbase, voff) do { _Pragma("unroll") for (int _i = 0; _i < 2; ++_i) \
;         __builtin_amdgcn_global_load_lds((const unsigned*)((const char*)(gbase) + (voff)[_i]), (LAS unsigned*)(lds + (bufoff) + ldsw + _i * 8192), 16, 0, 0); } while (0)
; #define PG8_LDA(dst, b, h) do { _Pragma("unroll") for (int m = 0; m < 4; ++m) _Pragma("unroll") for (int k = 0; k < 2; ++k) dst[m][k] = *(const LAS bf16x8*)(lds + PG8_SA(b, h) + aoff + m * 2048 + k * 1024); } while (0)
; #define PG8_LDB(dst, b, h) do { _Pragma("unroll") for (int n = 0; n < 2; ++n) _Pragma("unroll") for (int k = 0; k < 2; ++k) dst[n][k] = *(const LAS bf16x8*)(lds + PG8_SB(b, h) + boff + n * 2048 + k * 1024); } while (0)
; #define PG8_MMA(ai, bj, At, Bt) do { __builtin_amdgcn_s_setprio(1); _Pragma("unroll") for (int m = 0; m < 4; ++m) _Pragma("unroll") for (int n = 0; n < 2; ++n) _Pragma("unroll") for (int k = 0; k < 2; ++k) \
;         acc[ai][bj][m][n] = __builtin_amdgcn_mfma_f32_16x16x32_bf16(Bt[n][k], At[m][k], acc[ai][bj][m][n], 0, 0, 0); __builtin_amdgcn_s_setprio(0); } while (0)
; #define PG8_WAIT_V(n) asm volatile("s_waitcnt vmcnt(" #n ")" ::: "memory")
; #define PG8_WAIT_L(n) asm volatile("s_waitcnt lgkmcnt(" #n ")" ::: "memory")
; #define PG8_BAR __builtin_amdgcn_s_barrier()
; #define PG8_SCHED __builtin_amdgcn_sched_barrier(0)
; template <class Epi, class Sched, bool ALIGN_EPI = true>
; __device__ __forceinline__ void gemm_phase(LAS unsigned char* lds, const Gemm g, const Sched& S, const Epi& E) {
;     ...
;             PG8_WAIT_V(8); PG8_WAIT_L(0); PG8_BAR; PG8_MMA(1, 0, At, B0); PG8_MMA(1, 1, At, B1); PG8_BAR; PG8_SCHED;
;             PG8_LDB(B0, 1, 0); PG8_LDB(B1, 1, 1); PG8_SCHED; PG8_LDA(At, 1, 0); PG8_STAGE(PG8_SA(0, 1), a2 + hA, voffA);
;             PG8_WAIT_V(8); PG8_WAIT_L(0); PG8_BAR; PG8_MMA(0, 0, At, B0); PG8_MMA(0, 1, At, B1); PG8_BAR; PG8_SCHED;
	s_setprio 1
	s_waitcnt lgkmcnt(0)
	v_mfma_f32_16x16x32_bf16 v[120:123], v[136:139], v[212:215], 0
	v_mfma_f32_16x16x32_bf16 v[120:123], v[140:143], v[216:219], v[120:123]
	v_mfma_f32_16x16x32_bf16 v[116:119], v[144:147], v[212:215], 0
	v_mfma_f32_16x16x32_bf16 v[116:119], v[170:173], v[216:219], v[116:119]
	v_mfma_f32_16x16x32_bf16 v[96:99], v[136:139], v[220:223], 0
	v_mfma_f32_16x16x32_bf16 v[96:99], v[140:143], v[224:227], v[96:99]
	v_mfma_f32_16x16x32_bf16 v[92:95], v[144:147], v[220:223], 0
	v_mfma_f32_16x16x32_bf16 v[92:95], v[170:173], v[224:227], v[92:95]
	v_mfma_f32_16x16x32_bf16 v[64:67], v[136:139], v[228:231], 0
	v_mfma_f32_16x16x32_bf16 v[64:67], v[140:143], v[232:235], v[64:67]
	v_mfma_f32_16x16x32_bf16 v[60:63], v[144:147], v[228:231], 0
	v_mfma_f32_16x16x32_bf16 v[60:63], v[170:173], v[232:235], v[60:63]
	v_mfma_f32_16x16x32_bf16 v[24:27], v[136:139], v[236:239], 0
	v_mfma_f32_16x16x32_bf16 v[24:27], v[140:143], v[240:243], v[24:27]
	v_mfma_f32_16x16x32_bf16 v[20:23], v[144:147], v[236:239], 0
	v_mfma_f32_16x16x32_bf16 v[20:23], v[170:173], v[240:243], v[20:23]
	s_setprio 0
	s_setprio 1
	v_mfma_f32_16x16x32_bf16 v[112:115], v[174:177], v[212:215], 0
	v_mfma_f32_16x16x32_bf16 v[112:115], v[178:181], v[216:219], v[112:115]
	v_mfma_f32_16x16x32_bf16 v[108:111], v[182:185], v[212:215], 0
	v_mfma_f32_16x16x32_bf16 v[108:111], v[208:211], v[216:219], v[108:111]
	v_mfma_f32_16x16x32_bf16 v[88:91], v[174:177], v[220:223], 0
	v_mfma_f32_16x16x32_bf16 v[88:91], v[178:181], v[224:227], v[88:91]
	v_mfma_f32_16x16x32_bf16 v[84:87], v[182:185], v[220:223], 0
	v_mfma_f32_16x16x32_bf16 v[84:87], v[208:211], v[224:227], v[84:87]
	v_mfma_f32_16x16x32_bf16 v[48:51], v[174:177], v[228:231], 0
	v_mfma_f32_16x16x32_bf16 v[48:51], v[178:181], v[232:235], v[48:51]
	v_mfma_f32_16x16x32_bf16 v[44:47], v[182:185], v[228:231], 0
	v_mfma_f32_16x16x32_bf16 v[44:47], v[208:211], v[232:235], v[44:47]
	v_mfma_f32_16x16x32_bf16 v[16:19], v[174:177], v[236:239], 0
	v_mfma_f32_16x16x32_bf16 v[16:19], v[178:181], v[240:243], v[16:19]
	s_setprio 2
	s_barrier
	v_mfma_f32_16x16x32_bf16 v[12:15], v[182:185], v[236:239], 0
	v_mfma_f32_16x16x32_bf16 v[12:15], v[208:211], v[240:243], v[12:15]
	s_setprio 0
	s_add_i32 s25, 0, 0x18000
	v_add_u32_e32 v162, s25, v186
	s_add_i32 s26, 0, 0x1c000
	ds_read_b128 v[136:139], v162
	ds_read_b128 v[140:143], v162 offset:1024
	ds_read_b128 v[144:147], v162 offset:2048
	ds_read_b128 v[170:173], v162 offset:3072
	v_add_u32_e32 v162, s26, v186
	ds_read_b128 v[174:177], v162
	ds_read_b128 v[178:181], v162 offset:1024
	ds_read_b128 v[182:185], v162 offset:2048
	ds_read_b128 v[208:211], v162 offset:3072
	s_add_u32 s10, s64, 0x80000
	s_addc_u32 s11, s65, 0
	s_mov_b32 m0, s75
	v_lshl_add_u64 v[162:163], s[10:11], 0, v[0:1]
	ds_read_b128 v[212:215], v197 offset:32768
	ds_read_b128 v[216:219], v197 offset:33792
	ds_read_b128 v[220:223], v197 offset:34816
	ds_read_b128 v[224:227], v197 offset:35840
	ds_read_b128 v[228:231], v197 offset:36864
	ds_read_b128 v[232:235], v197 offset:37888
	ds_read_b128 v[236:239], v197 offset:38912
	ds_read_b128 v[240:243], v197 offset:39936
	global_load_lds_dwordx4 v[162:163], off
	v_lshl_add_u64 v[162:163], s[10:11], 0, v[148:149]
	s_mov_b32 m0, s76
	s_nop 0
	global_load_lds_dwordx4 v[162:163], off
	s_waitcnt vmcnt(8)
	s_waitcnt lgkmcnt(0)
	s_barrier
	s_setprio 1
	s_waitcnt lgkmcnt(0)
	v_mfma_f32_16x16x32_bf16 v[36:39], v[136:139], v[212:215], v[36:39]
	v_mfma_f32_16x16x32_bf16 v[36:39], v[140:143], v[216:219], v[36:39]
	v_mfma_f32_16x16x32_bf16 v[40:43], v[144:147], v[212:215], v[40:43]
	v_mfma_f32_16x16x32_bf16 v[40:43], v[170:173], v[216:219], v[40:43]
	v_mfma_f32_16x16x32_bf16 v[68:71], v[136:139], v[220:223], v[68:71]
	v_mfma_f32_16x16x32_bf16 v[68:71], v[140:143], v[224:227], v[68:71]
	v_mfma_f32_16x16x32_bf16 v[72:75], v[144:147], v[220:223], v[72:75]
	v_mfma_f32_16x16x32_bf16 v[72:75], v[170:173], v[224:227], v[72:75]
	v_mfma_f32_16x16x32_bf16 v[100:103], v[136:139], v[228:231], v[100:103]
	v_mfma_f32_16x16x32_bf16 v[100:103], v[140:143], v[232:235], v[100:103]
	v_mfma_f32_16x16x32_bf16 v[104:107], v[144:147], v[228:231], v[104:107]
	v_mfma_f32_16x16x32_bf16 v[104:107], v[170:173], v[232:235], v[104:107]
	v_mfma_f32_16x16x32_bf16 v[128:131], v[136:139], v[236:239], v[128:131]
	v_mfma_f32_16x16x32_bf16 v[128:131], v[140:143], v[240:243], v[128:131]
	v_mfma_f32_16x16x32_bf16 v[124:127], v[144:147], v[236:239], v[124:127]
	v_mfma_f32_16x16x32_bf16 v[124:127], v[170:173], v[240:243], v[124:127]
	s_setprio 0
	s_setprio 1
	v_mfma_f32_16x16x32_bf16 v[8:11], v[174:177], v[212:215], v[8:11]
	v_mfma_f32_16x16x32_bf16 v[8:11], v[178:181], v[216:219], v[8:11]
	v_mfma_f32_16x16x32_bf16 v[4:7], v[182:185], v[212:215], v[4:7]
	v_mfma_f32_16x16x32_bf16 v[4:7], v[208:211], v[216:219], v[4:7]
	v_mfma_f32_16x16x32_bf16 v[32:35], v[174:177], v[220:223], v[32:35]
	v_mfma_f32_16x16x32_bf16 v[32:35], v[178:181], v[224:227], v[32:35]
	v_mfma_f32_16x16x32_bf16 v[28:31], v[182:185], v[220:223], v[28:31]
	v_mfma_f32_16x16x32_bf16 v[28:31], v[208:211], v[224:227], v[28:31]
	v_mfma_f32_16x16x32_bf16 v[56:59], v[174:177], v[228:231], v[56:59]
	v_mfma_f32_16x16x32_bf16 v[56:59], v[178:181], v[232:235], v[56:59]
	v_mfma_f32_16x16x32_bf16 v[52:55], v[182:185], v[228:231], v[52:55]
	v_mfma_f32_16x16x32_bf16 v[52:55], v[208:211], v[232:235], v[52:55]
	v_mfma_f32_16x16x32_bf16 v[80:83], v[174:177], v[236:239], v[80:83]
	v_mfma_f32_16x16x32_bf16 v[80:83], v[178:181], v[240:243], v[80:83]
	s_setprio 2
	s_barrier
; #define PG8_STAGE(bufoff, gbase, voff) do { _Pragma("unroll") for (int _i = 0; _i < 2; ++_i) \
;         __builtin_amdgcn_global_load_lds((const unsigned*)((const char*)(gbase) + (voff)[_i]), (LAS unsigned*)(lds + (bufoff) + ldsw + _i * 8192), 16, 0, 0); } while (0)
; #define PG8_LDA(dst, b, h) do { _Pragma("unroll") for (int m = 0; m < 4; ++m) _Pragma("unroll") for (int k = 0; k < 2; ++k) dst[m][k] = *(const LAS bf16x8*)(lds + PG8_SA(b, h) + aoff + m * 2048 + k * 1024); } while (0)
; #define PG8_LDB(dst, b, h) do { _Pragma("unroll") for (int n = 0; n < 2; ++n) _Pragma("unroll") for (int k = 0; k < 2; ++k) dst[n][k] = *(const LAS bf16x8*)(lds + PG8_SB(b, h) + boff + n * 2048 + k * 1024); } while (0)
; #define PG8_MMA(ai, bj, At, Bt) do { __builtin_amdgcn_s_setprio(1); _Pragma("unroll") for (int m = 0; m < 4; ++m) _Pragma("unroll") for (int n = 0; n < 2; ++n) _Pragma("unroll") for (int k = 0; k < 2; ++k) \
;         acc[ai][bj][m][n] = __builtin_amdgcn_mfma_f32_16x16x32_bf16(Bt[n][k], At[m][k], acc[ai][bj][m][n], 0, 0, 0); __builtin_amdgcn_s_setprio(0); } while (0)
; #define PG8_WAIT_V(n) asm volatile("s_waitcnt vmcnt(" #n ")" ::: "memory")
; #define PG8_WAIT_L(n) asm volatile("s_waitcnt lgkmcnt(" #n ")" ::: "memory")
; #define PG8_BAR __builtin_amdgcn_s_barrier()
; #define PG8_SCHED __builtin_amdgcn_sched_barrier(0)
; template <class Epi, class Sched, bool ALIGN_EPI = true>
; __device__ __forceinline__ void gemm_phase(LAS unsigned char* lds, const Gemm g, const Sched& S, const Epi& E) {
;     ...
;             const bool last = (t == nt - 2);
;             const char* a1 = cA + (size_t)(t + 1) * kstep;
;             const char* a2 = last ? nA : cA + (size_t)(t + 2) * kstep; const char* b2 = last ? nB : cB + (size_t)(t + 2) * kstep;
;             const char* a3 = a2 + kstep; const char* b3 = b2 + kstep;
;             PG8_LDB(B0, 0, 0); PG8_LDB(B1, 0, 1); PG8_SCHED; PG8_LDA(At, 0, 0); PG8_STAGE(PG8_SA(1, 1), a1 + hA, voffA);
;     ...
;             PG8_WAIT_V(8); PG8_WAIT_L(0); PG8_BAR; PG8_MMA(0, 0, At, B0); PG8_MMA(0, 1, At, B1); PG8_BAR; PG8_SCHED;
;             PG8_LDA(At, 1, 1); PG8_STAGE(PG8_SB(1, 0), b3, voffB); PG8_STAGE(PG8_SB(1, 1), b3 + hB, voffB); PG8_STAGE(PG8_SA(1, 0), a3, voffA);
;             PG8_WAIT_V(8); PG8_WAIT_L(0); PG8_BAR; PG8_MMA(1, 0, At, B0); PG8_MMA(1, 1, At, B1); PG8_BAR; PG8_SCHED;
	v_mfma_f32_16x16x32_bf16 v[76:79], v[182:185], v[236:239], v[76:79]
	v_mfma_f32_16x16x32_bf16 v[76:79], v[208:211], v[240:243], v[76:79]
	s_setprio 0
	s_add_i32 s10, s25, s67
	v_lshl_add_u64 v[162:163], v[244:245], 0, s[86:87]
	s_mov_b32 m0, s10
	ds_read_b128 v[212:215], v197 offset:49152
	ds_read_b128 v[216:219], v197 offset:50176
	ds_read_b128 v[220:223], v197 offset:51200
	ds_read_b128 v[224:227], v197 offset:52224
	ds_read_b128 v[228:231], v197 offset:53248
	ds_read_b128 v[232:235], v197 offset:54272
	ds_read_b128 v[236:239], v197 offset:55296
	ds_read_b128 v[240:243], v197 offset:56320
	global_load_lds_dwordx4 v[162:163], off
	s_add_i32 m0, s10, 0x2000
	s_add_u32 s10, s62, 0x80080
	v_lshl_add_u64 v[162:163], v[246:247], 0, s[86:87]
	s_addc_u32 s11, s63, 0
	s_add_i32 s25, s26, s67
	global_load_lds_dwordx4 v[162:163], off
	v_lshl_add_u64 v[162:163], s[10:11], 0, v[2:3]
	s_mov_b32 m0, s25
	v_lshl_add_u64 v[160:161], v[160:161], 0, s[86:87]
	global_load_lds_dwordx4 v[162:163], off
	v_lshl_add_u64 v[162:163], s[10:11], 0, v[150:151]
	s_add_i32 m0, s25, 0x2000
	s_nop 0
	global_load_lds_dwordx4 v[162:163], off
	v_lshl_add_u64 v[162:163], v[248:249], 0, s[86:87]
	s_mov_b32 m0, s79
	s_nop 0
	global_load_lds_dwordx4 v[162:163], off
	s_mov_b32 m0, s80
	s_nop 0
	global_load_lds_dwordx4 v[160:161], off
	s_waitcnt vmcnt(8)
	s_waitcnt lgkmcnt(0)
	s_barrier
	s_setprio 1
	s_waitcnt lgkmcnt(0)
	v_mfma_f32_16x16x32_bf16 v[120:123], v[136:139], v[212:215], v[120:123]
	v_mfma_f32_16x16x32_bf16 v[120:123], v[140:143], v[216:219], v[120:123]
	s_add_i32 s24, s24, 2
	s_mov_b64 s[10:11], vcc
	s_add_u32 vcc_lo, s10, 0x100
	v_mfma_f32_16x16x32_bf16 v[116:119], v[144:147], v[212:215], v[116:119]
	v_mfma_f32_16x16x32_bf16 v[116:119], v[170:173], v[216:219], v[116:119]
	s_addc_u32 vcc_hi, s11, 0
	s_add_u32 s25, s18, s10
	v_mfma_f32_16x16x32_bf16 v[96:99], v[136:139], v[220:223], v[96:99]
	v_mfma_f32_16x16x32_bf16 v[96:99], v[140:143], v[224:227], v[96:99]
	s_addc_u32 s26, s19, s11
	s_add_i32 s27, 0, 0x10000
	v_mfma_f32_16x16x32_bf16 v[92:95], v[144:147], v[220:223], v[92:95]
	v_mfma_f32_16x16x32_bf16 v[92:95], v[170:173], v[224:227], v[92:95]
	s_cmp_eq_u32 s24, 28
	s_cselect_b32 s65, s16, s26
	v_mfma_f32_16x16x32_bf16 v[64:67], v[136:139], v[228:231], v[64:67]
	v_mfma_f32_16x16x32_bf16 v[64:67], v[140:143], v[232:235], v[64:67]
	s_cselect_b32 s26, 0, vcc_lo
	s_cselect_b32 s64, s17, s25
	v_mfma_f32_16x16x32_bf16 v[60:63], v[144:147], v[228:231], v[60:63]
	v_mfma_f32_16x16x32_bf16 v[60:63], v[170:173], v[232:235], v[60:63]
	s_cselect_b32 s25, 0, vcc_hi
	s_add_u32 s62, s14, s26
	v_mfma_f32_16x16x32_bf16 v[24:27], v[136:139], v[236:239], v[24:27]
	v_mfma_f32_16x16x32_bf16 v[24:27], v[140:143], v[240:243], v[24:27]
	s_addc_u32 s63, s15, s25
	s_add_i32 s25, 0, 0x14000
	v_mfma_f32_16x16x32_bf16 v[20:23], v[144:147], v[236:239], v[20:23]
	v_mfma_f32_16x16x32_bf16 v[20:23], v[170:173], v[240:243], v[20:23]
	s_setprio 0
	s_setprio 1
	v_mfma_f32_16x16x32_bf16 v[112:115], v[174:177], v[212:215], v[112:115]
	v_mfma_f32_16x16x32_bf16 v[112:115], v[178:181], v[216:219], v[112:115]
	v_mfma_f32_16x16x32_bf16 v[108:111], v[182:185], v[212:215], v[108:111]
	v_mfma_f32_16x16x32_bf16 v[108:111], v[208:211], v[216:219], v[108:111]
	v_mfma_f32_16x16x32_bf16 v[88:91], v[174:177], v[220:223], v[88:91]
	v_mfma_f32_16x16x32_bf16 v[88:91], v[178:181], v[224:227], v[88:91]
	v_mfma_f32_16x16x32_bf16 v[84:87], v[182:185], v[220:223], v[84:87]
	v_mfma_f32_16x16x32_bf16 v[84:87], v[208:211], v[224:227], v[84:87]
	v_mfma_f32_16x16x32_bf16 v[48:51], v[174:177], v[228:231], v[48:51]
	v_mfma_f32_16x16x32_bf16 v[48:51], v[178:181], v[232:235], v[48:51]
	v_mfma_f32_16x16x32_bf16 v[44:47], v[182:185], v[228:231], v[44:47]
	v_mfma_f32_16x16x32_bf16 v[44:47], v[208:211], v[232:235], v[44:47]
	v_mfma_f32_16x16x32_bf16 v[16:19], v[174:177], v[236:239], v[16:19]
	v_mfma_f32_16x16x32_bf16 v[16:19], v[178:181], v[240:243], v[16:19]
	s_setprio 2
	s_barrier
	v_mfma_f32_16x16x32_bf16 v[12:15], v[182:185], v[236:239], v[12:15]
	v_mfma_f32_16x16x32_bf16 v[12:15], v[208:211], v[240:243], v[12:15]
	s_setprio 0
	s_cmp_gt_u32 s24, 29
	s_cbranch_scc1 .Lpeel_exit_667
.LBB0_667:
	v_add_u32_e32 v160, s27, v186
	ds_read_b128 v[136:139], v160
	ds_read_b128 v[140:143], v160 offset:1024
	ds_read_b128 v[144:147], v160 offset:2048
	ds_read_b128 v[170:173], v160 offset:3072
	v_add_u32_e32 v160, s25, v186
	ds_read_b128 v[174:177], v160
	ds_read_b128 v[178:181], v160 offset:1024
	ds_read_b128 v[182:185], v160 offset:2048
	ds_read_b128 v[208:211], v160 offset:3072
	v_lshl_add_u64 v[244:245], v[132:133], 0, s[10:11]
	s_add_i32 m0, s53, 0xc000
	ds_read_b128 v[212:215], v197
	ds_read_b128 v[216:219], v197 offset:1024
	ds_read_b128 v[220:223], v197 offset:2048
	ds_read_b128 v[224:227], v197 offset:3072
	ds_read_b128 v[228:231], v197 offset:4096
	ds_read_b128 v[232:235], v197 offset:5120
	ds_read_b128 v[236:239], v197 offset:6144
	ds_read_b128 v[240:243], v197 offset:7168
	global_load_lds_dwordx4 v[244:245], off
	v_lshl_add_u64 v[244:245], v[134:135], 0, s[10:11]
	s_add_i32 m0, s53, 0xe000
	s_nop 0
	global_load_lds_dwordx4 v[244:245], off
	s_waitcnt vmcnt(8)
	s_waitcnt lgkmcnt(0)
	s_barrier
; #define PG8_STAGE(bufoff, gbase, voff) do { _Pragma("unroll") for (int _i = 0; _i < 2; ++_i) \
;         __builtin_amdgcn_global_load_lds((const unsigned*)((const char*)(gbase) + (voff)[_i]), (LAS unsigned*)(lds + (bufoff) + ldsw + _i * 8192), 16, 0, 0); } while (0)
; #define PG8_LDA(dst, b, h) do { _Pragma("unroll") for (int m = 0; m < 4; ++m) _Pragma("unroll") for (int k = 0; k < 2; ++k) dst[m][k] = *(const LAS bf16x8*)(lds + PG8_SA(b, h) + aoff + m * 2048 + k * 1024); } while (0)
; #define PG8_MMA(ai, bj, At, Bt) do { __builtin_amdgcn_s_setprio(1); _Pragma("unroll") for (int m = 0; m < 4; ++m) _Pragma("unroll") for (int n = 0; n < 2; ++n) _Pragma("unroll") for (int k = 0; k < 2; ++k) \
;         acc[ai][bj][m][n] = __builtin_amdgcn_mfma_f32_16x16x32_bf16(Bt[n][k], At[m][k], acc[ai][bj][m][n], 0, 0, 0); __builtin_amdgcn_s_setprio(0); } while (0)
; #define PG8_WAIT_V(n) asm volatile("s_waitcnt vmcnt(" #n ")" ::: "memory")
; #define PG8_WAIT_L(n) asm volatile("s_waitcnt lgkmcnt(" #n ")" ::: "memory")
; #define PG8_BAR __builtin_amdgcn_s_barrier()
; #define PG8_SCHED __builtin_amdgcn_sched_barrier(0)
; template <class Epi, class Sched, bool ALIGN_EPI = true>
; __device__ __forceinline__ void gemm_phase(LAS unsigned char* lds, const Gemm g, const Sched& S, const Epi& E) {
;     ...
;             PG8_WAIT_V(8); PG8_WAIT_L(0); PG8_BAR; PG8_MMA(0, 0, At, B0); PG8_MMA(0, 1, At, B1); PG8_BAR; PG8_SCHED;
;             PG8_LDA(At, 0, 1); PG8_STAGE(PG8_SB(0, 0), b2, voffB); PG8_STAGE(PG8_SB(0, 1), b2 + hB, voffB); PG8_STAGE(PG8_SA(0, 0), a2, voffA);
;             PG8_WAIT_V(8); PG8_WAIT_L(0); PG8_BAR; PG8_MMA(1, 0, At, B0); PG8_MMA(1, 1, At, B1); PG8_BAR; PG8_SCHED;
	s_setprio 1
	s_waitcnt lgkmcnt(0)
	v_mfma_f32_16x16x32_bf16 v[36:39], v[136:139], v[212:215], v[36:39]
	v_mfma_f32_16x16x32_bf16 v[36:39], v[140:143], v[216:219], v[36:39]
	v_mfma_f32_16x16x32_bf16 v[40:43], v[144:147], v[212:215], v[40:43]
	v_mfma_f32_16x16x32_bf16 v[40:43], v[170:173], v[216:219], v[40:43]
	v_mfma_f32_16x16x32_bf16 v[68:71], v[136:139], v[220:223], v[68:71]
	v_mfma_f32_16x16x32_bf16 v[68:71], v[140:143], v[224:227], v[68:71]
	v_mfma_f32_16x16x32_bf16 v[72:75], v[144:147], v[220:223], v[72:75]
	v_mfma_f32_16x16x32_bf16 v[72:75], v[170:173], v[224:227], v[72:75]
	v_mfma_f32_16x16x32_bf16 v[100:103], v[136:139], v[228:231], v[100:103]
	v_mfma_f32_16x16x32_bf16 v[100:103], v[140:143], v[232:235], v[100:103]
	v_mfma_f32_16x16x32_bf16 v[104:107], v[144:147], v[228:231], v[104:107]
	v_mfma_f32_16x16x32_bf16 v[104:107], v[170:173], v[232:235], v[104:107]
	v_mfma_f32_16x16x32_bf16 v[128:131], v[136:139], v[236:239], v[128:131]
	v_mfma_f32_16x16x32_bf16 v[128:131], v[140:143], v[240:243], v[128:131]
	v_mfma_f32_16x16x32_bf16 v[124:127], v[144:147], v[236:239], v[124:127]
	v_mfma_f32_16x16x32_bf16 v[124:127], v[170:173], v[240:243], v[124:127]
	s_setprio 0
	s_setprio 1
	v_mfma_f32_16x16x32_bf16 v[8:11], v[174:177], v[212:215], v[8:11]
	v_mfma_f32_16x16x32_bf16 v[8:11], v[178:181], v[216:219], v[8:11]
	v_mfma_f32_16x16x32_bf16 v[4:7], v[182:185], v[212:215], v[4:7]
	v_mfma_f32_16x16x32_bf16 v[4:7], v[208:211], v[216:219], v[4:7]
	v_mfma_f32_16x16x32_bf16 v[32:35], v[174:177], v[220:223], v[32:35]
	v_mfma_f32_16x16x32_bf16 v[32:35], v[178:181], v[224:227], v[32:35]
	v_mfma_f32_16x16x32_bf16 v[28:31], v[182:185], v[220:223], v[28:31]
	v_mfma_f32_16x16x32_bf16 v[28:31], v[208:211], v[224:227], v[28:31]
	v_mfma_f32_16x16x32_bf16 v[56:59], v[174:177], v[228:231], v[56:59]
	v_mfma_f32_16x16x32_bf16 v[56:59], v[178:181], v[232:235], v[56:59]
	v_mfma_f32_16x16x32_bf16 v[52:55], v[182:185], v[228:231], v[52:55]
	v_mfma_f32_16x16x32_bf16 v[52:55], v[208:211], v[232:235], v[52:55]
	v_mfma_f32_16x16x32_bf16 v[80:83], v[174:177], v[236:239], v[80:83]
	v_mfma_f32_16x16x32_bf16 v[80:83], v[178:181], v[240:243], v[80:83]
	s_setprio 2
	s_barrier
	v_mfma_f32_16x16x32_bf16 v[76:79], v[182:185], v[236:239], v[76:79]
	v_mfma_f32_16x16x32_bf16 v[76:79], v[208:211], v[240:243], v[76:79]
	s_setprio 0
	s_add_i32 s10, s27, s67
	v_lshl_add_u64 v[244:245], s[62:63], 0, v[2:3]
	s_mov_b32 m0, s10
	ds_read_b128 v[212:215], v197 offset:16384
	ds_read_b128 v[216:219], v197 offset:17408
	ds_read_b128 v[220:223], v197 offset:18432
	ds_read_b128 v[224:227], v197 offset:19456
	ds_read_b128 v[228:231], v197 offset:20480
	ds_read_b128 v[232:235], v197 offset:21504
	ds_read_b128 v[236:239], v197 offset:22528
	ds_read_b128 v[240:243], v197 offset:23552
	global_load_lds_dwordx4 v[244:245], off
	s_add_i32 m0, s10, 0x2000
	s_add_u32 s10, s62, 0x80000
	v_lshl_add_u64 v[246:247], s[62:63], 0, v[150:151]
	s_addc_u32 s11, s63, 0
	s_add_i32 s25, s25, s67
	global_load_lds_dwordx4 v[246:247], off
	v_lshl_add_u64 v[248:249], s[10:11], 0, v[2:3]
	s_mov_b32 m0, s25
	v_lshl_add_u64 v[160:161], s[64:65], 0, v[148:149]
	global_load_lds_dwordx4 v[248:249], off
	v_lshl_add_u64 v[248:249], s[10:11], 0, v[150:151]
	s_add_i32 m0, s25, 0x2000
	s_nop 0
	global_load_lds_dwordx4 v[248:249], off
	v_lshl_add_u64 v[248:249], s[64:65], 0, v[0:1]
	s_mov_b32 m0, s53
	s_nop 0
	global_load_lds_dwordx4 v[248:249], off
	s_mov_b32 m0, s66
	s_nop 0
	global_load_lds_dwordx4 v[160:161], off
	s_waitcnt vmcnt(8)
	s_waitcnt lgkmcnt(0)
	s_barrier
	s_setprio 1
	s_waitcnt lgkmcnt(0)
	v_mfma_f32_16x16x32_bf16 v[120:123], v[136:139], v[212:215], v[120:123]
	v_mfma_f32_16x16x32_bf16 v[120:123], v[140:143], v[216:219], v[120:123]
	v_mfma_f32_16x16x32_bf16 v[116:119], v[144:147], v[212:215], v[116:119]
	v_mfma_f32_16x16x32_bf16 v[116:119], v[170:173], v[216:219], v[116:119]
	v_mfma_f32_16x16x32_bf16 v[96:99], v[136:139], v[220:223], v[96:99]
	v_mfma_f32_16x16x32_bf16 v[96:99], v[140:143], v[224:227], v[96:99]
	v_mfma_f32_16x16x32_bf16 v[92:95], v[144:147], v[220:223], v[92:95]
	v_mfma_f32_16x16x32_bf16 v[92:95], v[170:173], v[224:227], v[92:95]
	v_mfma_f32_16x16x32_bf16 v[64:67], v[136:139], v[228:231], v[64:67]
	v_mfma_f32_16x16x32_bf16 v[64:67], v[140:143], v[232:235], v[64:67]
	v_mfma_f32_16x16x32_bf16 v[60:63], v[144:147], v[228:231], v[60:63]
	v_mfma_f32_16x16x32_bf16 v[60:63], v[170:173], v[232:235], v[60:63]
	v_mfma_f32_16x16x32_bf16 v[24:27], v[136:139], v[236:239], v[24:27]
	v_mfma_f32_16x16x32_bf16 v[24:27], v[140:143], v[240:243], v[24:27]
	v_mfma_f32_16x16x32_bf16 v[20:23], v[144:147], v[236:239], v[20:23]
	v_mfma_f32_16x16x32_bf16 v[20:23], v[170:173], v[240:243], v[20:23]
	s_setprio 0
	s_setprio 1
	v_mfma_f32_16x16x32_bf16 v[112:115], v[174:177], v[212:215], v[112:115]
	v_mfma_f32_16x16x32_bf16 v[112:115], v[178:181], v[216:219], v[112:115]
	v_mfma_f32_16x16x32_bf16 v[108:111], v[182:185], v[212:215], v[108:111]
	v_mfma_f32_16x16x32_bf16 v[108:111], v[208:211], v[216:219], v[108:111]
	v_mfma_f32_16x16x32_bf16 v[88:91], v[174:177], v[220:223], v[88:91]
	v_mfma_f32_16x16x32_bf16 v[88:91], v[178:181], v[224:227], v[88:91]
	v_mfma_f32_16x16x32_bf16 v[84:87], v[182:185], v[220:223], v[84:87]
	v_mfma_f32_16x16x32_bf16 v[84:87], v[208:211], v[224:227], v[84:87]
	v_mfma_f32_16x16x32_bf16 v[48:51], v[174:177], v[228:231], v[48:51]
	v_mfma_f32_16x16x32_bf16 v[48:51], v[178:181], v[232:235], v[48:51]
	v_mfma_f32_16x16x32_bf16 v[44:47], v[182:185], v[228:231], v[44:47]
	v_mfma_f32_16x16x32_bf16 v[44:47], v[208:211], v[232:235], v[44:47]
	v_mfma_f32_16x16x32_bf16 v[16:19], v[174:177], v[236:239], v[16:19]
	v_mfma_f32_16x16x32_bf16 v[16:19], v[178:181], v[240:243], v[16:19]
	s_setprio 2
	s_barrier
; #define PG8_STAGE(bufoff, gbase, voff) do { _Pragma("unroll") for (int _i = 0; _i < 2; ++_i) \
;         __builtin_amdgcn_global_load_lds((const unsigned*)((const char*)(gbase) + (voff)[_i]), (LAS unsigned*)(lds + (bufoff) + ldsw + _i * 8192), 16, 0, 0); } while (0)
; #define PG8_LDA(dst, b, h) do { _Pragma("unroll") for (int m = 0; m < 4; ++m) _Pragma("unroll") for (int k = 0; k < 2; ++k) dst[m][k] = *(const LAS bf16x8*)(lds + PG8_SA(b, h) + aoff + m * 2048 + k * 1024); } while (0)
; #define PG8_LDB(dst, b, h) do { _Pragma("unroll") for (int n = 0; n < 2; ++n) _Pragma("unroll") for (int k = 0; k < 2; ++k) dst[n][k] = *(const LAS bf16x8*)(lds + PG8_SB(b, h) + boff + n * 2048 + k * 1024); } while (0)
; #define PG8_MMA(ai, bj, At, Bt) do { __builtin_amdgcn_s_setprio(1); _Pragma("unroll") for (int m = 0; m < 4; ++m) _Pragma("unroll") for (int n = 0; n < 2; ++n) _Pragma("unroll") for (int k = 0; k < 2; ++k) \
;         acc[ai][bj][m][n] = __builtin_amdgcn_mfma_f32_16x16x32_bf16(Bt[n][k], At[m][k], acc[ai][bj][m][n], 0, 0, 0); __builtin_amdgcn_s_setprio(0); } while (0)
; #define PG8_WAIT_V(n) asm volatile("s_waitcnt vmcnt(" #n ")" ::: "memory")
; #define PG8_WAIT_L(n) asm volatile("s_waitcnt lgkmcnt(" #n ")" ::: "memory")
; #define PG8_BAR __builtin_amdgcn_s_barrier()
; #define PG8_SCHED __builtin_amdgcn_sched_barrier(0)
; template <class Epi, class Sched, bool ALIGN_EPI = true>
; __device__ __forceinline__ void gemm_phase(LAS unsigned char* lds, const Gemm g, const Sched& S, const Epi& E) {
;     ...
;             PG8_WAIT_V(8); PG8_WAIT_L(0); PG8_BAR; PG8_MMA(1, 0, At, B0); PG8_MMA(1, 1, At, B1); PG8_BAR; PG8_SCHED;
;             PG8_LDB(B0, 1, 0); PG8_LDB(B1, 1, 1); PG8_SCHED; PG8_LDA(At, 1, 0); PG8_STAGE(PG8_SA(0, 1), a2 + hA, voffA);
;             PG8_WAIT_V(8); PG8_WAIT_L(0); PG8_BAR; PG8_MMA(0, 0, At, B0); PG8_MMA(0, 1, At, B1); PG8_BAR; PG8_SCHED;
	v_mfma_f32_16x16x32_bf16 v[12:15], v[182:185], v[236:239], v[12:15]
	v_mfma_f32_16x16x32_bf16 v[12:15], v[208:211], v[240:243], v[12:15]
	s_setprio 0
	s_add_i32 s25, 0, 0x18000
	v_add_u32_e32 v162, s25, v186
	s_add_i32 s26, 0, 0x1c000
	ds_read_b128 v[136:139], v162
	ds_read_b128 v[140:143], v162 offset:1024
	ds_read_b128 v[144:147], v162 offset:2048
	ds_read_b128 v[170:173], v162 offset:3072
	v_add_u32_e32 v162, s26, v186
	ds_read_b128 v[174:177], v162
	ds_read_b128 v[178:181], v162 offset:1024
	ds_read_b128 v[182:185], v162 offset:2048
	ds_read_b128 v[208:211], v162 offset:3072
	s_add_u32 s10, s64, 0x80000
	s_addc_u32 s11, s65, 0
	s_mov_b32 m0, s75
	v_lshl_add_u64 v[162:163], s[10:11], 0, v[0:1]
	ds_read_b128 v[212:215], v197 offset:32768
	ds_read_b128 v[216:219], v197 offset:33792
	ds_read_b128 v[220:223], v197 offset:34816
	ds_read_b128 v[224:227], v197 offset:35840
	ds_read_b128 v[228:231], v197 offset:36864
	ds_read_b128 v[232:235], v197 offset:37888
	ds_read_b128 v[236:239], v197 offset:38912
	ds_read_b128 v[240:243], v197 offset:39936
	global_load_lds_dwordx4 v[162:163], off
	v_lshl_add_u64 v[162:163], s[10:11], 0, v[148:149]
	s_mov_b32 m0, s76
	s_nop 0
	global_load_lds_dwordx4 v[162:163], off
	s_waitcnt vmcnt(8)
	s_waitcnt lgkmcnt(0)
	s_barrier
	s_setprio 1
	s_waitcnt lgkmcnt(0)
	v_mfma_f32_16x16x32_bf16 v[36:39], v[136:139], v[212:215], v[36:39]
	v_mfma_f32_16x16x32_bf16 v[36:39], v[140:143], v[216:219], v[36:39]
	v_mfma_f32_16x16x32_bf16 v[40:43], v[144:147], v[212:215], v[40:43]
	v_mfma_f32_16x16x32_bf16 v[40:43], v[170:173], v[216:219], v[40:43]
	v_mfma_f32_16x16x32_bf16 v[68:71], v[136:139], v[220:223], v[68:71]
	v_mfma_f32_16x16x32_bf16 v[68:71], v[140:143], v[224:227], v[68:71]
	v_mfma_f32_16x16x32_bf16 v[72:75], v[144:147], v[220:223], v[72:75]
	v_mfma_f32_16x16x32_bf16 v[72:75], v[170:173], v[224:227], v[72:75]
	v_mfma_f32_16x16x32_bf16 v[100:103], v[136:139], v[228:231], v[100:103]
	v_mfma_f32_16x16x32_bf16 v[100:103], v[140:143], v[232:235], v[100:103]
	v_mfma_f32_16x16x32_bf16 v[104:107], v[144:147], v[228:231], v[104:107]
	v_mfma_f32_16x16x32_bf16 v[104:107], v[170:173], v[232:235], v[104:107]
	v_mfma_f32_16x16x32_bf16 v[128:131], v[136:139], v[236:239], v[128:131]
	v_mfma_f32_16x16x32_bf16 v[128:131], v[140:143], v[240:243], v[128:131]
	v_mfma_f32_16x16x32_bf16 v[124:127], v[144:147], v[236:239], v[124:127]
	v_mfma_f32_16x16x32_bf16 v[124:127], v[170:173], v[240:243], v[124:127]
	s_setprio 0
	s_setprio 1
	v_mfma_f32_16x16x32_bf16 v[8:11], v[174:177], v[212:215], v[8:11]
	v_mfma_f32_16x16x32_bf16 v[8:11], v[178:181], v[216:219], v[8:11]
	v_mfma_f32_16x16x32_bf16 v[4:7], v[182:185], v[212:215], v[4:7]
	v_mfma_f32_16x16x32_bf16 v[4:7], v[208:211], v[216:219], v[4:7]
	v_mfma_f32_16x16x32_bf16 v[32:35], v[174:177], v[220:223], v[32:35]
	v_mfma_f32_16x16x32_bf16 v[32:35], v[178:181], v[224:227], v[32:35]
	v_mfma_f32_16x16x32_bf16 v[28:31], v[182:185], v[220:223], v[28:31]
	v_mfma_f32_16x16x32_bf16 v[28:31], v[208:211], v[224:227], v[28:31]
	v_mfma_f32_16x16x32_bf16 v[56:59], v[174:177], v[228:231], v[56:59]
	v_mfma_f32_16x16x32_bf16 v[56:59], v[178:181], v[232:235], v[56:59]
	v_mfma_f32_16x16x32_bf16 v[52:55], v[182:185], v[228:231], v[52:55]
	v_mfma_f32_16x16x32_bf16 v[52:55], v[208:211], v[232:235], v[52:55]
	v_mfma_f32_16x16x32_bf16 v[80:83], v[174:177], v[236:239], v[80:83]
	v_mfma_f32_16x16x32_bf16 v[80:83], v[178:181], v[240:243], v[80:83]
	s_setprio 2
	s_barrier
; #define PG8_STAGE(bufoff, gbase, voff) do { _Pragma("unroll") for (int _i = 0; _i < 2; ++_i) \
;         __builtin_amdgcn_global_load_lds((const unsigned*)((const char*)(gbase) + (voff)[_i]), (LAS unsigned*)(lds + (bufoff) + ldsw + _i * 8192), 16, 0, 0); } while (0)
; #define PG8_LDA(dst, b, h) do { _Pragma("unroll") for (int m = 0; m < 4; ++m) _Pragma("unroll") for (int k = 0; k < 2; ++k) dst[m][k] = *(const LAS bf16x8*)(lds + PG8_SA(b, h) + aoff + m * 2048 + k * 1024); } while (0)
; #define PG8_MMA(ai, bj, At, Bt) do { __builtin_amdgcn_s_setprio(1); _Pragma("unroll") for (int m = 0; m < 4; ++m) _Pragma("unroll") for (int n = 0; n < 2; ++n) _Pragma("unroll") for (int k = 0; k < 2; ++k) \
;         acc[ai][bj][m][n] = __builtin_amdgcn_mfma_f32_16x16x32_bf16(Bt[n][k], At[m][k], acc[ai][bj][m][n], 0, 0, 0); __builtin_amdgcn_s_setprio(0); } while (0)
; #define PG8_WAIT_V(n) asm volatile("s_waitcnt vmcnt(" #n ")" ::: "memory")
; #define PG8_WAIT_L(n) asm volatile("s_waitcnt lgkmcnt(" #n ")" ::: "memory")
; #define PG8_BAR __builtin_amdgcn_s_barrier()
; #define PG8_SCHED __builtin_amdgcn_sched_barrier(0)
; template <class Epi, class Sched, bool ALIGN_EPI = true>
; __device__ __forceinline__ void gemm_phase(LAS unsigned char* lds, const Gemm g, const Sched& S, const Epi& E) {
;     ...
;             const bool last = (t == nt - 2);
;             const char* a1 = cA + (size_t)(t + 1) * kstep;
;             const char* a2 = last ? nA : cA + (size_t)(t + 2) * kstep; const char* b2 = last ? nB : cB + (size_t)(t + 2) * kstep;
;             const char* a3 = a2 + kstep; const char* b3 = b2 + kstep;
;     ...
;             PG8_WAIT_V(8); PG8_WAIT_L(0); PG8_BAR; PG8_MMA(0, 0, At, B0); PG8_MMA(0, 1, At, B1); PG8_BAR; PG8_SCHED;
;             PG8_LDA(At, 1, 1); PG8_STAGE(PG8_SB(1, 0), b3, voffB); PG8_STAGE(PG8_SB(1, 1), b3 + hB, voffB); PG8_STAGE(PG8_SA(1, 0), a3, voffA);
;             PG8_WAIT_V(8); PG8_WAIT_L(0); PG8_BAR; PG8_MMA(1, 0, At, B0); PG8_MMA(1, 1, At, B1); PG8_BAR; PG8_SCHED;
	v_mfma_f32_16x16x32_bf16 v[76:79], v[182:185], v[236:239], v[76:79]
	v_mfma_f32_16x16x32_bf16 v[76:79], v[208:211], v[240:243], v[76:79]
	s_setprio 0
	s_add_i32 s10, s25, s67
	v_lshl_add_u64 v[162:163], v[244:245], 0, s[86:87]
	s_mov_b32 m0, s10
	ds_read_b128 v[212:215], v197 offset:49152
	ds_read_b128 v[216:219], v197 offset:50176
	ds_read_b128 v[220:223], v197 offset:51200
	ds_read_b128 v[224:227], v197 offset:52224
	ds_read_b128 v[228:231], v197 offset:53248
	ds_read_b128 v[232:235], v197 offset:54272
	ds_read_b128 v[236:239], v197 offset:55296
	ds_read_b128 v[240:243], v197 offset:56320
	global_load_lds_dwordx4 v[162:163], off
	s_add_i32 m0, s10, 0x2000
	s_add_u32 s10, s62, 0x80080
	v_lshl_add_u64 v[162:163], v[246:247], 0, s[86:87]
	s_addc_u32 s11, s63, 0
	s_add_i32 s25, s26, s67
	global_load_lds_dwordx4 v[162:163], off
	v_lshl_add_u64 v[162:163], s[10:11], 0, v[2:3]
	s_mov_b32 m0, s25
	v_lshl_add_u64 v[160:161], v[160:161], 0, s[86:87]
	global_load_lds_dwordx4 v[162:163], off
	v_lshl_add_u64 v[162:163], s[10:11], 0, v[150:151]
	s_add_i32 m0, s25, 0x2000
	s_nop 0
	global_load_lds_dwordx4 v[162:163], off
	v_lshl_add_u64 v[162:163], v[248:249], 0, s[86:87]
	s_mov_b32 m0, s79
	s_nop 0
	global_load_lds_dwordx4 v[162:163], off
	s_mov_b32 m0, s80
	s_nop 0
	global_load_lds_dwordx4 v[160:161], off
	s_waitcnt vmcnt(8)
	s_waitcnt lgkmcnt(0)
	s_barrier
	s_setprio 1
	s_waitcnt lgkmcnt(0)
	v_mfma_f32_16x16x32_bf16 v[120:123], v[136:139], v[212:215], v[120:123]
	v_mfma_f32_16x16x32_bf16 v[120:123], v[140:143], v[216:219], v[120:123]
	s_add_i32 s24, s24, 2
	s_mov_b64 s[10:11], vcc
	s_add_u32 vcc_lo, s10, 0x100
	v_mfma_f32_16x16x32_bf16 v[116:119], v[144:147], v[212:215], v[116:119]
	v_mfma_f32_16x16x32_bf16 v[116:119], v[170:173], v[216:219], v[116:119]
	s_addc_u32 vcc_hi, s11, 0
	s_add_u32 s25, s18, s10
	v_mfma_f32_16x16x32_bf16 v[96:99], v[136:139], v[220:223], v[96:99]
	v_mfma_f32_16x16x32_bf16 v[96:99], v[140:143], v[224:227], v[96:99]
	s_addc_u32 s26, s19, s11
	s_add_i32 s27, 0, 0x10000
	v_mfma_f32_16x16x32_bf16 v[92:95], v[144:147], v[220:223], v[92:95]
	v_mfma_f32_16x16x32_bf16 v[92:95], v[170:173], v[224:227], v[92:95]
	s_cmp_eq_u32 s24, 28
	s_cselect_b32 s65, s16, s26
	v_mfma_f32_16x16x32_bf16 v[64:67], v[136:139], v[228:231], v[64:67]
	v_mfma_f32_16x16x32_bf16 v[64:67], v[140:143], v[232:235], v[64:67]
	s_cselect_b32 s26, 0, vcc_lo
	s_cselect_b32 s64, s17, s25
	v_mfma_f32_16x16x32_bf16 v[60:63], v[144:147], v[228:231], v[60:63]
	v_mfma_f32_16x16x32_bf16 v[60:63], v[170:173], v[232:235], v[60:63]
	s_cselect_b32 s25, 0, vcc_hi
	s_add_u32 s62, s14, s26
	v_mfma_f32_16x16x32_bf16 v[24:27], v[136:139], v[236:239], v[24:27]
	v_mfma_f32_16x16x32_bf16 v[24:27], v[140:143], v[240:243], v[24:27]
	s_addc_u32 s63, s15, s25
	s_add_i32 s25, 0, 0x14000
	v_mfma_f32_16x16x32_bf16 v[20:23], v[144:147], v[236:239], v[20:23]
	v_mfma_f32_16x16x32_bf16 v[20:23], v[170:173], v[240:243], v[20:23]
	s_setprio 0
	s_setprio 1
	v_mfma_f32_16x16x32_bf16 v[112:115], v[174:177], v[212:215], v[112:115]
	v_mfma_f32_16x16x32_bf16 v[112:115], v[178:181], v[216:219], v[112:115]
	v_mfma_f32_16x16x32_bf16 v[108:111], v[182:185], v[212:215], v[108:111]
	v_mfma_f32_16x16x32_bf16 v[108:111], v[208:211], v[216:219], v[108:111]
	v_mfma_f32_16x16x32_bf16 v[88:91], v[174:177], v[220:223], v[88:91]
	v_mfma_f32_16x16x32_bf16 v[88:91], v[178:181], v[224:227], v[88:91]
	v_mfma_f32_16x16x32_bf16 v[84:87], v[182:185], v[220:223], v[84:87]
	v_mfma_f32_16x16x32_bf16 v[84:87], v[208:211], v[224:227], v[84:87]
	v_mfma_f32_16x16x32_bf16 v[48:51], v[174:177], v[228:231], v[48:51]
	v_mfma_f32_16x16x32_bf16 v[48:51], v[178:181], v[232:235], v[48:51]
	v_mfma_f32_16x16x32_bf16 v[44:47], v[182:185], v[228:231], v[44:47]
	v_mfma_f32_16x16x32_bf16 v[44:47], v[208:211], v[232:235], v[44:47]
	v_mfma_f32_16x16x32_bf16 v[16:19], v[174:177], v[236:239], v[16:19]
	v_mfma_f32_16x16x32_bf16 v[16:19], v[178:181], v[240:243], v[16:19]
	s_setprio 2
	s_barrier
	v_mfma_f32_16x16x32_bf16 v[12:15], v[182:185], v[236:239], v[12:15]
	v_mfma_f32_16x16x32_bf16 v[12:15], v[208:211], v[240:243], v[12:15]
	s_setprio 0
	s_cmp_gt_u32 s24, 29
	s_cbranch_scc0 .LBB0_667

;     __device__ bool next(int i, Unit& u) const { if (i >= 2) return false; const int x = c & 7, j = c >> 3; u.pm = 32 * i + 4 * x + (j & 3); u.pn = j >> 2; return true; }
; #define PG8_STAGE(bufoff, gbase, voff) do { _Pragma("unroll") for (int _i = 0; _i < 2; ++_i) \
;         __builtin_amdgcn_global_load_lds((const unsigned*)((const char*)(gbase) + (voff)[_i]), (LAS unsigned*)(lds + (bufoff) + ldsw + _i * 8192), 16, 0, 0); } while (0)
; #define PG8_LDA(dst, b, h) do { _Pragma("unroll") for (int m = 0; m < 4; ++m) _Pragma("unroll") for (int k = 0; k < 2; ++k) dst[m][k] = *(const LAS bf16x8*)(lds + PG8_SA(b, h) + aoff + m * 2048 + k * 1024); } while (0)
; #define PG8_LDB(dst, b, h) do { _Pragma("unroll") for (int n = 0; n < 2; ++n) _Pragma("unroll") for (int k = 0; k < 2; ++k) dst[n][k] = *(const LAS bf16x8*)(lds + PG8_SB(b, h) + boff + n * 2048 + k * 1024); } while (0)
; #define PG8_WAIT_V(n) asm volatile("s_waitcnt vmcnt(" #n ")" ::: "memory")
; #define PG8_WAIT_L(n) asm volatile("s_waitcnt lgkmcnt(" #n ")" ::: "memory")
; #define PG8_BAR __builtin_amdgcn_s_barrier()
; #define PG8_SCHED __builtin_amdgcn_sched_barrier(0)
; template <class Epi, class Sched, bool ALIGN_EPI = true>
; __device__ __forceinline__ void gemm_phase(LAS unsigned char* lds, const Gemm g, const Sched& S, const Epi& E) {
;     ...
;         const bool has_next = S.next(ui + 1, nxt);
;         const char* nA = has_next ? (const char*)g.A + ((size_t)nxt.pm * BM * g.lda + (size_t)nxt.pn * g.a_pn_off) * 2 : cA; const char* nB = has_next ? (const char*)g.Bt + (size_t)nxt.pn * BM * g.ldb * 2 : cB;
;         for (int t = 0; t < nt; t += 2) {
;             const bool last = (t == nt - 2);
;             const char* a1 = cA + (size_t)(t + 1) * kstep;
;             const char* a2 = last ? nA : cA + (size_t)(t + 2) * kstep; const char* b2 = last ? nB : cB + (size_t)(t + 2) * kstep;
;             const char* a3 = a2 + kstep; const char* b3 = b2 + kstep;
;             PG8_LDB(B0, 0, 0); PG8_LDB(B1, 0, 1); PG8_SCHED; PG8_LDA(At, 0, 0); PG8_STAGE(PG8_SA(1, 1), a1 + hA, voffA);
;             PG8_WAIT_V(8); PG8_WAIT_L(0); PG8_BAR; PG8_MMA(0, 0, At, B0); PG8_MMA(0, 1, At, B1); PG8_BAR; PG8_SCHED;
;             PG8_LDA(At, 0, 1); PG8_STAGE(PG8_SB(0, 0), b2, voffB); PG8_STAGE(PG8_SB(0, 1), b2 + hB, voffB); PG8_STAGE(PG8_SA(0, 0), a2, voffA);
.LBB0_1110:
	s_add_u32 s16, s10, 0x100
	s_addc_u32 s17, s11, 0
	s_add_u32 s10, s10, 0x160080
	s_addc_u32 s11, s11, 0
	v_lshl_add_u64 v[132:133], s[10:11], 0, v[168:169]
	v_lshl_add_u64 v[134:135], s[10:11], 0, v[170:171]
	s_mov_b32 s18, -2
	s_mov_b64 s[10:11], 0
	s_add_u32 vcc_lo, s10, 0x100
	s_addc_u32 vcc_hi, s11, 0
	s_add_u32 s19, s16, s10
	s_addc_u32 s24, s17, s11
	s_add_i32 s25, 0, 0x10000
	s_cmpk_eq_i32 s18, 0x54
	s_cselect_b32 s65, s61, s24
	s_cselect_b32 s24, 0, vcc_lo
	s_cselect_b32 s64, s60, s19
	s_cselect_b32 s19, 0, vcc_hi
	s_add_u32 s62, s2, s24
	v_add_u32_e32 v160, s25, v188
	s_addc_u32 s63, s3, s19
	s_add_i32 s19, 0, 0x14000
	ds_read_b128 v[136:139], v160
	ds_read_b128 v[140:143], v160 offset:1024
	ds_read_b128 v[144:147], v160 offset:2048
	ds_read_b128 v[172:175], v160 offset:3072
	v_add_u32_e32 v160, s19, v188
	ds_read_b128 v[176:179], v160
	ds_read_b128 v[180:183], v160 offset:1024
	ds_read_b128 v[184:187], v160 offset:2048
	ds_read_b128 v[208:211], v160 offset:3072
	v_lshl_add_u64 v[160:161], v[132:133], 0, s[10:11]
	s_add_i32 m0, s67, 0xc000
	ds_read_b128 v[212:215], v197
	ds_read_b128 v[216:219], v197 offset:1024
	ds_read_b128 v[220:223], v197 offset:2048
	ds_read_b128 v[224:227], v197 offset:3072
	ds_read_b128 v[228:231], v197 offset:4096
	ds_read_b128 v[232:235], v197 offset:5120
	ds_read_b128 v[236:239], v197 offset:6144
	ds_read_b128 v[240:243], v197 offset:7168
	global_load_lds_dwordx4 v[160:161], off
	v_lshl_add_u64 v[160:161], v[134:135], 0, s[10:11]
	s_add_i32 m0, s67, 0xe000
	s_nop 0
	global_load_lds_dwordx4 v[160:161], off
	s_waitcnt vmcnt(8)
	s_waitcnt lgkmcnt(0)
	s_barrier
	s_setprio 1
	s_waitcnt lgkmcnt(0)
	v_mfma_f32_16x16x32_bf16 v[16:19], v[136:139], v[212:215], 0
	v_mfma_f32_16x16x32_bf16 v[16:19], v[140:143], v[216:219], v[16:19]
	v_mfma_f32_16x16x32_bf16 v[12:15], v[144:147], v[212:215], 0
	v_mfma_f32_16x16x32_bf16 v[12:15], v[172:175], v[216:219], v[12:15]
	v_mfma_f32_16x16x32_bf16 v[56:59], v[136:139], v[220:223], 0
	v_mfma_f32_16x16x32_bf16 v[56:59], v[140:143], v[224:227], v[56:59]
	v_mfma_f32_16x16x32_bf16 v[52:55], v[144:147], v[220:223], 0
	v_mfma_f32_16x16x32_bf16 v[52:55], v[172:175], v[224:227], v[52:55]
	v_mfma_f32_16x16x32_bf16 v[88:91], v[136:139], v[228:231], 0
	v_mfma_f32_16x16x32_bf16 v[88:91], v[140:143], v[232:235], v[88:91]
	v_mfma_f32_16x16x32_bf16 v[76:79], v[144:147], v[228:231], 0
	v_mfma_f32_16x16x32_bf16 v[76:79], v[172:175], v[232:235], v[76:79]
	v_mfma_f32_16x16x32_bf16 v[112:115], v[136:139], v[236:239], 0
	v_mfma_f32_16x16x32_bf16 v[112:115], v[140:143], v[240:243], v[112:115]
	v_mfma_f32_16x16x32_bf16 v[108:111], v[144:147], v[236:239], 0
	v_mfma_f32_16x16x32_bf16 v[108:111], v[172:175], v[240:243], v[108:111]
	s_setprio 0
	s_setprio 1
	v_mfma_f32_16x16x32_bf16 v[8:11], v[176:179], v[212:215], 0
	v_mfma_f32_16x16x32_bf16 v[8:11], v[180:183], v[216:219], v[8:11]
	v_mfma_f32_16x16x32_bf16 v[4:7], v[184:187], v[212:215], 0
	v_mfma_f32_16x16x32_bf16 v[4:7], v[208:211], v[216:219], v[4:7]
	v_mfma_f32_16x16x32_bf16 v[40:43], v[176:179], v[220:223], 0
	v_mfma_f32_16x16x32_bf16 v[40:43], v[180:183], v[224:227], v[40:43]
	v_mfma_f32_16x16x32_bf16 v[36:39], v[184:187], v[220:223], 0
	v_mfma_f32_16x16x32_bf16 v[36:39], v[208:211], v[224:227], v[36:39]
	v_mfma_f32_16x16x32_bf16 v[64:67], v[176:179], v[228:231], 0
	v_mfma_f32_16x16x32_bf16 v[64:67], v[180:183], v[232:235], v[64:67]
	v_mfma_f32_16x16x32_bf16 v[60:63], v[184:187], v[228:231], 0
	v_mfma_f32_16x16x32_bf16 v[60:63], v[208:211], v[232:235], v[60:63]
	v_mfma_f32_16x16x32_bf16 v[96:99], v[176:179], v[236:239], 0
	v_mfma_f32_16x16x32_bf16 v[96:99], v[180:183], v[240:243], v[96:99]
	s_setprio 2
	s_barrier
	v_mfma_f32_16x16x32_bf16 v[92:95], v[184:187], v[236:239], 0
	v_mfma_f32_16x16x32_bf16 v[92:95], v[208:211], v[240:243], v[92:95]
	s_setprio 0
	s_add_i32 s10, s25, s66
	v_lshl_add_u64 v[160:161], s[62:63], 0, v[2:3]
	s_mov_b32 m0, s10
	ds_read_b128 v[212:215], v197 offset:16384
	ds_read_b128 v[216:219], v197 offset:17408
	ds_read_b128 v[220:223], v197 offset:18432
	ds_read_b128 v[224:227], v197 offset:19456
	ds_read_b128 v[228:231], v197 offset:20480
	ds_read_b128 v[232:235], v197 offset:21504
	ds_read_b128 v[236:239], v197 offset:22528
	ds_read_b128 v[240:243], v197 offset:23552
	global_load_lds_dwordx4 v[160:161], off
	s_add_i32 m0, s10, 0x2000
	s_add_u32 s10, s62, 0x160000
	v_lshl_add_u64 v[162:163], s[62:63], 0, v[150:151]
	s_addc_u32 s11, s63, 0
	s_add_i32 s19, s19, s66
	global_load_lds_dwordx4 v[162:163], off
	v_lshl_add_u64 v[244:245], s[10:11], 0, v[2:3]
	s_mov_b32 m0, s19
	v_lshl_add_u64 v[246:247], s[64:65], 0, v[148:149]
	global_load_lds_dwordx4 v[244:245], off
	v_lshl_add_u64 v[244:245], s[10:11], 0, v[150:151]
	s_add_i32 m0, s19, 0x2000
	s_nop 0
	global_load_lds_dwordx4 v[244:245], off
	v_lshl_add_u64 v[244:245], s[64:65], 0, v[0:1]
	s_mov_b32 m0, s67
	s_nop 0
	global_load_lds_dwordx4 v[244:245], off
	s_mov_b32 m0, s75
	s_nop 0
	global_load_lds_dwordx4 v[246:247], off
	s_waitcnt vmcnt(8)
	s_waitcnt lgkmcnt(0)
	s_barrier
; #define PG8_STAGE(bufoff, gbase, voff) do { _Pragma("unroll") for (int _i = 0; _i < 2; ++_i) \
;         __builtin_amdgcn_global_load_lds((const unsigned*)((const char*)(gbase) + (voff)[_i]), (LAS unsigned*)(lds + (bufoff) + ldsw + _i * 8192), 16, 0, 0); } while (0)
; #define PG8_LDA(dst, b, h) do { _Pragma("unroll") for (int m = 0; m < 4; ++m) _Pragma("unroll") for (int k = 0; k < 2; ++k) dst[m][k] = *(const LAS bf16x8*)(lds + PG8_SA(b, h) + aoff + m * 2048 + k * 1024); } while (0)
; #define PG8_LDB(dst, b, h) do { _Pragma("unroll") for (int n = 0; n < 2; ++n) _Pragma("unroll") for (int k = 0; k < 2; ++k) dst[n][k] = *(const LAS bf16x8*)(lds + PG8_SB(b, h) + boff + n * 2048 + k * 1024); } while (0)
; #define PG8_MMA(ai, bj, At, Bt) do { __builtin_amdgcn_s_setprio(1); _Pragma("unroll") for (int m = 0; m < 4; ++m) _Pragma("unroll") for (int n = 0; n < 2; ++n) _Pragma("unroll") for (int k = 0; k < 2; ++k) \
;         acc[ai][bj][m][n] = __builtin_amdgcn_mfma_f32_16x16x32_bf16(Bt[n][k], At[m][k], acc[ai][bj][m][n], 0, 0, 0); __builtin_amdgcn_s_setprio(0); } while (0)
; #define PG8_WAIT_V(n) asm volatile("s_waitcnt vmcnt(" #n ")" ::: "memory")
; #define PG8_WAIT_L(n) asm volatile("s_waitcnt lgkmcnt(" #n ")" ::: "memory")
; #define PG8_BAR __builtin_amdgcn_s_barrier()
; #define PG8_SCHED __builtin_amdgcn_sched_barrier(0)
; template <class Epi, class Sched, bool ALIGN_EPI = true>
; __device__ __forceinline__ void gemm_phase(LAS unsigned char* lds, const Gemm g, const Sched& S, const Epi& E) {
;     ...
;             PG8_WAIT_V(8); PG8_WAIT_L(0); PG8_BAR; PG8_MMA(1, 0, At, B0); PG8_MMA(1, 1, At, B1); PG8_BAR; PG8_SCHED;
;             PG8_LDB(B0, 1, 0); PG8_LDB(B1, 1, 1); PG8_SCHED; PG8_LDA(At, 1, 0); PG8_STAGE(PG8_SA(0, 1), a2 + hA, voffA);
;             PG8_WAIT_V(8); PG8_WAIT_L(0); PG8_BAR; PG8_MMA(0, 0, At, B0); PG8_MMA(0, 1, At, B1); PG8_BAR; PG8_SCHED;
	s_setprio 1
	s_waitcnt lgkmcnt(0)
	v_mfma_f32_16x16x32_bf16 v[128:131], v[136:139], v[212:215], 0
	v_mfma_f32_16x16x32_bf16 v[128:131], v[140:143], v[216:219], v[128:131]
	v_mfma_f32_16x16x32_bf16 v[124:127], v[144:147], v[212:215], 0
	v_mfma_f32_16x16x32_bf16 v[124:127], v[172:175], v[216:219], v[124:127]
	v_mfma_f32_16x16x32_bf16 v[104:107], v[136:139], v[220:223], 0
	v_mfma_f32_16x16x32_bf16 v[104:107], v[140:143], v[224:227], v[104:107]
	v_mfma_f32_16x16x32_bf16 v[100:103], v[144:147], v[220:223], 0
	v_mfma_f32_16x16x32_bf16 v[100:103], v[172:175], v[224:227], v[100:103]
	v_mfma_f32_16x16x32_bf16 v[72:75], v[136:139], v[228:231], 0
	v_mfma_f32_16x16x32_bf16 v[72:75], v[140:143], v[232:235], v[72:75]
	v_mfma_f32_16x16x32_bf16 v[68:71], v[144:147], v[228:231], 0
	v_mfma_f32_16x16x32_bf16 v[68:71], v[172:175], v[232:235], v[68:71]
	v_mfma_f32_16x16x32_bf16 v[32:35], v[136:139], v[236:239], 0
	v_mfma_f32_16x16x32_bf16 v[32:35], v[140:143], v[240:243], v[32:35]
	v_mfma_f32_16x16x32_bf16 v[28:31], v[144:147], v[236:239], 0
	v_mfma_f32_16x16x32_bf16 v[28:31], v[172:175], v[240:243], v[28:31]
	s_setprio 0
	s_setprio 1
	v_mfma_f32_16x16x32_bf16 v[120:123], v[176:179], v[212:215], 0
	v_mfma_f32_16x16x32_bf16 v[120:123], v[180:183], v[216:219], v[120:123]
	v_mfma_f32_16x16x32_bf16 v[116:119], v[184:187], v[212:215], 0
	v_mfma_f32_16x16x32_bf16 v[116:119], v[208:211], v[216:219], v[116:119]
	v_mfma_f32_16x16x32_bf16 v[84:87], v[176:179], v[220:223], 0
	v_mfma_f32_16x16x32_bf16 v[84:87], v[180:183], v[224:227], v[84:87]
	v_mfma_f32_16x16x32_bf16 v[80:83], v[184:187], v[220:223], 0
	v_mfma_f32_16x16x32_bf16 v[80:83], v[208:211], v[224:227], v[80:83]
	v_mfma_f32_16x16x32_bf16 v[48:51], v[176:179], v[228:231], 0
	v_mfma_f32_16x16x32_bf16 v[48:51], v[180:183], v[232:235], v[48:51]
	v_mfma_f32_16x16x32_bf16 v[44:47], v[184:187], v[228:231], 0
	v_mfma_f32_16x16x32_bf16 v[44:47], v[208:211], v[232:235], v[44:47]
	v_mfma_f32_16x16x32_bf16 v[24:27], v[176:179], v[236:239], 0
	v_mfma_f32_16x16x32_bf16 v[24:27], v[180:183], v[240:243], v[24:27]
	s_setprio 2
	s_barrier
	v_mfma_f32_16x16x32_bf16 v[20:23], v[184:187], v[236:239], 0
	v_mfma_f32_16x16x32_bf16 v[20:23], v[208:211], v[240:243], v[20:23]
	s_setprio 0
	s_add_i32 s19, 0, 0x18000
	s_add_i32 s24, 0, 0x1c000
	v_add_u32_e32 v172, s19, v188
	v_add_u32_e32 v207, s24, v188
	ds_read_b128 v[136:139], v172
	ds_read_b128 v[140:143], v172 offset:1024
	ds_read_b128 v[144:147], v172 offset:2048
	ds_read_b128 v[172:175], v172 offset:3072
	ds_read_b128 v[176:179], v207
	ds_read_b128 v[180:183], v207 offset:1024
	ds_read_b128 v[184:187], v207 offset:2048
	ds_read_b128 v[208:211], v207 offset:3072
	s_add_u32 s10, s64, 0x160000
	s_addc_u32 s11, s65, 0
	s_mov_b32 m0, s76
	v_lshl_add_u64 v[248:249], s[10:11], 0, v[0:1]
	ds_read_b128 v[212:215], v197 offset:32768
	ds_read_b128 v[216:219], v197 offset:33792
	ds_read_b128 v[220:223], v197 offset:34816
	ds_read_b128 v[224:227], v197 offset:35840
	ds_read_b128 v[228:231], v197 offset:36864
	ds_read_b128 v[232:235], v197 offset:37888
	ds_read_b128 v[236:239], v197 offset:38912
	ds_read_b128 v[240:243], v197 offset:39936
	global_load_lds_dwordx4 v[248:249], off
	v_lshl_add_u64 v[248:249], s[10:11], 0, v[148:149]
	s_mov_b32 m0, s77
	s_nop 0
	global_load_lds_dwordx4 v[248:249], off
	s_waitcnt vmcnt(8)
	s_waitcnt lgkmcnt(0)
	s_barrier
	s_setprio 1
	s_waitcnt lgkmcnt(0)
	v_mfma_f32_16x16x32_bf16 v[16:19], v[136:139], v[212:215], v[16:19]
	v_mfma_f32_16x16x32_bf16 v[16:19], v[140:143], v[216:219], v[16:19]
	v_mfma_f32_16x16x32_bf16 v[12:15], v[144:147], v[212:215], v[12:15]
	v_mfma_f32_16x16x32_bf16 v[12:15], v[172:175], v[216:219], v[12:15]
	v_mfma_f32_16x16x32_bf16 v[56:59], v[136:139], v[220:223], v[56:59]
	v_mfma_f32_16x16x32_bf16 v[56:59], v[140:143], v[224:227], v[56:59]
	v_mfma_f32_16x16x32_bf16 v[52:55], v[144:147], v[220:223], v[52:55]
	v_mfma_f32_16x16x32_bf16 v[52:55], v[172:175], v[224:227], v[52:55]
	v_mfma_f32_16x16x32_bf16 v[88:91], v[136:139], v[228:231], v[88:91]
	v_mfma_f32_16x16x32_bf16 v[88:91], v[140:143], v[232:235], v[88:91]
	v_mfma_f32_16x16x32_bf16 v[76:79], v[144:147], v[228:231], v[76:79]
	v_mfma_f32_16x16x32_bf16 v[76:79], v[172:175], v[232:235], v[76:79]
	v_mfma_f32_16x16x32_bf16 v[112:115], v[136:139], v[236:239], v[112:115]
	v_mfma_f32_16x16x32_bf16 v[112:115], v[140:143], v[240:243], v[112:115]
	v_mfma_f32_16x16x32_bf16 v[108:111], v[144:147], v[236:239], v[108:111]
	v_mfma_f32_16x16x32_bf16 v[108:111], v[172:175], v[240:243], v[108:111]
	s_setprio 0
	s_setprio 1
	v_mfma_f32_16x16x32_bf16 v[8:11], v[176:179], v[212:215], v[8:11]
	v_mfma_f32_16x16x32_bf16 v[8:11], v[180:183], v[216:219], v[8:11]
	v_mfma_f32_16x16x32_bf16 v[4:7], v[184:187], v[212:215], v[4:7]
	v_mfma_f32_16x16x32_bf16 v[4:7], v[208:211], v[216:219], v[4:7]
	v_mfma_f32_16x16x32_bf16 v[40:43], v[176:179], v[220:223], v[40:43]
	v_mfma_f32_16x16x32_bf16 v[40:43], v[180:183], v[224:227], v[40:43]
	v_mfma_f32_16x16x32_bf16 v[36:39], v[184:187], v[220:223], v[36:39]
	v_mfma_f32_16x16x32_bf16 v[36:39], v[208:211], v[224:227], v[36:39]
	v_mfma_f32_16x16x32_bf16 v[64:67], v[176:179], v[228:231], v[64:67]
	v_mfma_f32_16x16x32_bf16 v[64:67], v[180:183], v[232:235], v[64:67]
	v_mfma_f32_16x16x32_bf16 v[60:63], v[184:187], v[228:231], v[60:63]
	v_mfma_f32_16x16x32_bf16 v[60:63], v[208:211], v[232:235], v[60:63]
	v_mfma_f32_16x16x32_bf16 v[96:99], v[176:179], v[236:239], v[96:99]
	v_mfma_f32_16x16x32_bf16 v[96:99], v[180:183], v[240:243], v[96:99]
	s_setprio 2
	s_barrier
; #define PG8_STAGE(bufoff, gbase, voff) do { _Pragma("unroll") for (int _i = 0; _i < 2; ++_i) \
;         __builtin_amdgcn_global_load_lds((const unsigned*)((const char*)(gbase) + (voff)[_i]), (LAS unsigned*)(lds + (bufoff) + ldsw + _i * 8192), 16, 0, 0); } while (0)
; #define PG8_LDA(dst, b, h) do { _Pragma("unroll") for (int m = 0; m < 4; ++m) _Pragma("unroll") for (int k = 0; k < 2; ++k) dst[m][k] = *(const LAS bf16x8*)(lds + PG8_SA(b, h) + aoff + m * 2048 + k * 1024); } while (0)
; #define PG8_LDB(dst, b, h) do { _Pragma("unroll") for (int n = 0; n < 2; ++n) _Pragma("unroll") for (int k = 0; k < 2; ++k) dst[n][k] = *(const LAS bf16x8*)(lds + PG8_SB(b, h) + boff + n * 2048 + k * 1024); } while (0)
; #define PG8_MMA(ai, bj, At, Bt) do { __builtin_amdgcn_s_setprio(1); _Pragma("unroll") for (int m = 0; m < 4; ++m) _Pragma("unroll") for (int n = 0; n < 2; ++n) _Pragma("unroll") for (int k = 0; k < 2; ++k) \
;         acc[ai][bj][m][n] = __builtin_amdgcn_mfma_f32_16x16x32_bf16(Bt[n][k], At[m][k], acc[ai][bj][m][n], 0, 0, 0); __builtin_amdgcn_s_setprio(0); } while (0)
; #define PG8_WAIT_V(n) asm volatile("s_waitcnt vmcnt(" #n ")" ::: "memory")
; #define PG8_WAIT_L(n) asm volatile("s_waitcnt lgkmcnt(" #n ")" ::: "memory")
; #define PG8_BAR __builtin_amdgcn_s_barrier()
; #define PG8_SCHED __builtin_amdgcn_sched_barrier(0)
; template <class Epi, class Sched, bool ALIGN_EPI = true>
; __device__ __forceinline__ void gemm_phase(LAS unsigned char* lds, const Gemm g, const Sched& S, const Epi& E) {
;     ...
;             const bool last = (t == nt - 2);
;             const char* a1 = cA + (size_t)(t + 1) * kstep;
;             const char* a2 = last ? nA : cA + (size_t)(t + 2) * kstep; const char* b2 = last ? nB : cB + (size_t)(t + 2) * kstep;
;             const char* a3 = a2 + kstep; const char* b3 = b2 + kstep;
;             PG8_LDB(B0, 0, 0); PG8_LDB(B1, 0, 1); PG8_SCHED; PG8_LDA(At, 0, 0); PG8_STAGE(PG8_SA(1, 1), a1 + hA, voffA);
;     ...
;             PG8_WAIT_V(8); PG8_WAIT_L(0); PG8_BAR; PG8_MMA(0, 0, At, B0); PG8_MMA(0, 1, At, B1); PG8_BAR; PG8_SCHED;
;             PG8_LDA(At, 1, 1); PG8_STAGE(PG8_SB(1, 0), b3, voffB); PG8_STAGE(PG8_SB(1, 1), b3 + hB, voffB); PG8_STAGE(PG8_SA(1, 0), a3, voffA);
;             PG8_WAIT_V(8); PG8_WAIT_L(0); PG8_BAR; PG8_MMA(1, 0, At, B0); PG8_MMA(1, 1, At, B1); PG8_BAR; PG8_SCHED;
	v_mfma_f32_16x16x32_bf16 v[92:95], v[184:187], v[236:239], v[92:95]
	v_mfma_f32_16x16x32_bf16 v[92:95], v[208:211], v[240:243], v[92:95]
	s_setprio 0
	s_add_i32 s10, s19, s66
	v_lshl_add_u64 v[160:161], v[160:161], 0, s[86:87]
	s_mov_b32 m0, s10
	ds_read_b128 v[212:215], v197 offset:49152
	ds_read_b128 v[216:219], v197 offset:50176
	ds_read_b128 v[220:223], v197 offset:51200
	ds_read_b128 v[224:227], v197 offset:52224
	ds_read_b128 v[228:231], v197 offset:53248
	ds_read_b128 v[232:235], v197 offset:54272
	ds_read_b128 v[236:239], v197 offset:55296
	ds_read_b128 v[240:243], v197 offset:56320
	global_load_lds_dwordx4 v[160:161], off
	s_add_i32 m0, s10, 0x2000
	s_add_u32 s10, s62, 0x160080
	v_lshl_add_u64 v[160:161], v[162:163], 0, s[86:87]
	s_addc_u32 s11, s63, 0
	s_add_i32 s19, s24, s66
	global_load_lds_dwordx4 v[160:161], off
	v_lshl_add_u64 v[160:161], s[10:11], 0, v[2:3]
	s_mov_b32 m0, s19
	s_nop 0
	global_load_lds_dwordx4 v[160:161], off
	v_lshl_add_u64 v[160:161], s[10:11], 0, v[150:151]
	s_add_i32 m0, s19, 0x2000
	s_nop 0
	global_load_lds_dwordx4 v[160:161], off
	v_lshl_add_u64 v[160:161], v[244:245], 0, s[86:87]
	s_mov_b32 m0, s80
	s_nop 0
	global_load_lds_dwordx4 v[160:161], off
	v_lshl_add_u64 v[160:161], v[246:247], 0, s[86:87]
	s_mov_b32 m0, s81
	s_nop 0
	global_load_lds_dwordx4 v[160:161], off
	s_waitcnt vmcnt(8)
	s_waitcnt lgkmcnt(0)
	s_barrier
	s_setprio 1
	s_waitcnt lgkmcnt(0)
	v_mfma_f32_16x16x32_bf16 v[128:131], v[136:139], v[212:215], v[128:131]
	v_mfma_f32_16x16x32_bf16 v[128:131], v[140:143], v[216:219], v[128:131]
	s_add_i32 s18, s18, 2
	s_mov_b64 s[10:11], vcc
	s_add_u32 vcc_lo, s10, 0x100
	v_mfma_f32_16x16x32_bf16 v[124:127], v[144:147], v[212:215], v[124:127]
	v_mfma_f32_16x16x32_bf16 v[124:127], v[172:175], v[216:219], v[124:127]
	s_addc_u32 vcc_hi, s11, 0
	s_add_u32 s19, s16, s10
	v_mfma_f32_16x16x32_bf16 v[104:107], v[136:139], v[220:223], v[104:107]
	v_mfma_f32_16x16x32_bf16 v[104:107], v[140:143], v[224:227], v[104:107]
	s_addc_u32 s24, s17, s11
	s_add_i32 s25, 0, 0x10000
	v_mfma_f32_16x16x32_bf16 v[100:103], v[144:147], v[220:223], v[100:103]
	v_mfma_f32_16x16x32_bf16 v[100:103], v[172:175], v[224:227], v[100:103]
	s_cmpk_eq_i32 s18, 0x54
	s_cselect_b32 s65, s61, s24
	v_mfma_f32_16x16x32_bf16 v[72:75], v[136:139], v[228:231], v[72:75]
	v_mfma_f32_16x16x32_bf16 v[72:75], v[140:143], v[232:235], v[72:75]
	s_cselect_b32 s24, 0, vcc_lo
	s_cselect_b32 s64, s60, s19
	v_mfma_f32_16x16x32_bf16 v[68:71], v[144:147], v[228:231], v[68:71]
	v_mfma_f32_16x16x32_bf16 v[68:71], v[172:175], v[232:235], v[68:71]
	s_cselect_b32 s19, 0, vcc_hi
	s_add_u32 s62, s2, s24
	v_mfma_f32_16x16x32_bf16 v[32:35], v[136:139], v[236:239], v[32:35]
	v_mfma_f32_16x16x32_bf16 v[32:35], v[140:143], v[240:243], v[32:35]
	s_addc_u32 s63, s3, s19
	s_add_i32 s19, 0, 0x14000
	v_mfma_f32_16x16x32_bf16 v[28:31], v[144:147], v[236:239], v[28:31]
	v_mfma_f32_16x16x32_bf16 v[28:31], v[172:175], v[240:243], v[28:31]
	s_setprio 0
	s_setprio 1
	v_mfma_f32_16x16x32_bf16 v[120:123], v[176:179], v[212:215], v[120:123]
	v_mfma_f32_16x16x32_bf16 v[120:123], v[180:183], v[216:219], v[120:123]
	v_mfma_f32_16x16x32_bf16 v[116:119], v[184:187], v[212:215], v[116:119]
	v_mfma_f32_16x16x32_bf16 v[116:119], v[208:211], v[216:219], v[116:119]
	v_mfma_f32_16x16x32_bf16 v[84:87], v[176:179], v[220:223], v[84:87]
	v_mfma_f32_16x16x32_bf16 v[84:87], v[180:183], v[224:227], v[84:87]
	v_mfma_f32_16x16x32_bf16 v[80:83], v[184:187], v[220:223], v[80:83]
	v_mfma_f32_16x16x32_bf16 v[80:83], v[208:211], v[224:227], v[80:83]
	v_mfma_f32_16x16x32_bf16 v[48:51], v[176:179], v[228:231], v[48:51]
	v_mfma_f32_16x16x32_bf16 v[48:51], v[180:183], v[232:235], v[48:51]
	v_mfma_f32_16x16x32_bf16 v[44:47], v[184:187], v[228:231], v[44:47]
	v_mfma_f32_16x16x32_bf16 v[44:47], v[208:211], v[232:235], v[44:47]
	v_mfma_f32_16x16x32_bf16 v[24:27], v[176:179], v[236:239], v[24:27]
	v_mfma_f32_16x16x32_bf16 v[24:27], v[180:183], v[240:243], v[24:27]
	s_setprio 2
	s_barrier
	v_mfma_f32_16x16x32_bf16 v[20:23], v[184:187], v[236:239], v[20:23]
	v_mfma_f32_16x16x32_bf16 v[20:23], v[208:211], v[240:243], v[20:23]
	s_setprio 0
	s_cmpk_gt_u32 s18, 0x55
	s_cbranch_scc1 .Lpeel_exit_1111
.LBB0_1111:
	v_add_u32_e32 v160, s25, v188
	ds_read_b128 v[136:139], v160
	ds_read_b128 v[140:143], v160 offset:1024
	ds_read_b128 v[144:147], v160 offset:2048
	ds_read_b128 v[172:175], v160 offset:3072
	v_add_u32_e32 v160, s19, v188
	ds_read_b128 v[176:179], v160
	ds_read_b128 v[180:183], v160 offset:1024
	ds_read_b128 v[184:187], v160 offset:2048
	ds_read_b128 v[208:211], v160 offset:3072
	v_lshl_add_u64 v[160:161], v[132:133], 0, s[10:11]
	s_add_i32 m0, s67, 0xc000
	ds_read_b128 v[212:215], v197
	ds_read_b128 v[216:219], v197 offset:1024
	ds_read_b128 v[220:223], v197 offset:2048
	ds_read_b128 v[224:227], v197 offset:3072
	ds_read_b128 v[228:231], v197 offset:4096
	ds_read_b128 v[232:235], v197 offset:5120
	ds_read_b128 v[236:239], v197 offset:6144
	ds_read_b128 v[240:243], v197 offset:7168
	global_load_lds_dwordx4 v[160:161], off
	v_lshl_add_u64 v[160:161], v[134:135], 0, s[10:11]
	s_add_i32 m0, s67, 0xe000
	s_nop 0
	global_load_lds_dwordx4 v[160:161], off
	s_waitcnt vmcnt(8)
	s_waitcnt lgkmcnt(0)
	s_barrier
; #define PG8_STAGE(bufoff, gbase, voff) do { _Pragma("unroll") for (int _i = 0; _i < 2; ++_i) \
;         __builtin_amdgcn_global_load_lds((const unsigned*)((const char*)(gbase) + (voff)[_i]), (LAS unsigned*)(lds + (bufoff) + ldsw + _i * 8192), 16, 0, 0); } while (0)
; #define PG8_LDA(dst, b, h) do { _Pragma("unroll") for (int m = 0; m < 4; ++m) _Pragma("unroll") for (int k = 0; k < 2; ++k) dst[m][k] = *(const LAS bf16x8*)(lds + PG8_SA(b, h) + aoff + m * 2048 + k * 1024); } while (0)
; #define PG8_MMA(ai, bj, At, Bt) do { __builtin_amdgcn_s_setprio(1); _Pragma("unroll") for (int m = 0; m < 4; ++m) _Pragma("unroll") for (int n = 0; n < 2; ++n) _Pragma("unroll") for (int k = 0; k < 2; ++k) \
;         acc[ai][bj][m][n] = __builtin_amdgcn_mfma_f32_16x16x32_bf16(Bt[n][k], At[m][k], acc[ai][bj][m][n], 0, 0, 0); __builtin_amdgcn_s_setprio(0); } while (0)
; #define PG8_WAIT_V(n) asm volatile("s_waitcnt vmcnt(" #n ")" ::: "memory")
; #define PG8_WAIT_L(n) asm volatile("s_waitcnt lgkmcnt(" #n ")" ::: "memory")
; #define PG8_BAR __builtin_amdgcn_s_barrier()
; #define PG8_SCHED __builtin_amdgcn_sched_barrier(0)
; template <class Epi, class Sched, bool ALIGN_EPI = true>
; __device__ __forceinline__ void gemm_phase(LAS unsigned char* lds, const Gemm g, const Sched& S, const Epi& E) {
;     ...
;             PG8_WAIT_V(8); PG8_WAIT_L(0); PG8_BAR; PG8_MMA(0, 0, At, B0); PG8_MMA(0, 1, At, B1); PG8_BAR; PG8_SCHED;
;             PG8_LDA(At, 0, 1); PG8_STAGE(PG8_SB(0, 0), b2, voffB); PG8_STAGE(PG8_SB(0, 1), b2 + hB, voffB); PG8_STAGE(PG8_SA(0, 0), a2, voffA);
;             PG8_WAIT_V(8); PG8_WAIT_L(0); PG8_BAR; PG8_MMA(1, 0, At, B0); PG8_MMA(1, 1, At, B1); PG8_BAR; PG8_SCHED;
	s_setprio 1
	s_waitcnt lgkmcnt(0)
	v_mfma_f32_16x16x32_bf16 v[16:19], v[136:139], v[212:215], v[16:19]
	v_mfma_f32_16x16x32_bf16 v[16:19], v[140:143], v[216:219], v[16:19]
	v_mfma_f32_16x16x32_bf16 v[12:15], v[144:147], v[212:215], v[12:15]
	v_mfma_f32_16x16x32_bf16 v[12:15], v[172:175], v[216:219], v[12:15]
	v_mfma_f32_16x16x32_bf16 v[56:59], v[136:139], v[220:223], v[56:59]
	v_mfma_f32_16x16x32_bf16 v[56:59], v[140:143], v[224:227], v[56:59]
	v_mfma_f32_16x16x32_bf16 v[52:55], v[144:147], v[220:223], v[52:55]
	v_mfma_f32_16x16x32_bf16 v[52:55], v[172:175], v[224:227], v[52:55]
	v_mfma_f32_16x16x32_bf16 v[88:91], v[136:139], v[228:231], v[88:91]
	v_mfma_f32_16x16x32_bf16 v[88:91], v[140:143], v[232:235], v[88:91]
	v_mfma_f32_16x16x32_bf16 v[76:79], v[144:147], v[228:231], v[76:79]
	v_mfma_f32_16x16x32_bf16 v[76:79], v[172:175], v[232:235], v[76:79]
	v_mfma_f32_16x16x32_bf16 v[112:115], v[136:139], v[236:239], v[112:115]
	v_mfma_f32_16x16x32_bf16 v[112:115], v[140:143], v[240:243], v[112:115]
	v_mfma_f32_16x16x32_bf16 v[108:111], v[144:147], v[236:239], v[108:111]
	v_mfma_f32_16x16x32_bf16 v[108:111], v[172:175], v[240:243], v[108:111]
	s_setprio 0
	s_setprio 1
	v_mfma_f32_16x16x32_bf16 v[8:11], v[176:179], v[212:215], v[8:11]
	v_mfma_f32_16x16x32_bf16 v[8:11], v[180:183], v[216:219], v[8:11]
	v_mfma_f32_16x16x32_bf16 v[4:7], v[184:187], v[212:215], v[4:7]
	v_mfma_f32_16x16x32_bf16 v[4:7], v[208:211], v[216:219], v[4:7]
	v_mfma_f32_16x16x32_bf16 v[40:43], v[176:179], v[220:223], v[40:43]
	v_mfma_f32_16x16x32_bf16 v[40:43], v[180:183], v[224:227], v[40:43]
	v_mfma_f32_16x16x32_bf16 v[36:39], v[184:187], v[220:223], v[36:39]
	v_mfma_f32_16x16x32_bf16 v[36:39], v[208:211], v[224:227], v[36:39]
	v_mfma_f32_16x16x32_bf16 v[64:67], v[176:179], v[228:231], v[64:67]
	v_mfma_f32_16x16x32_bf16 v[64:67], v[180:183], v[232:235], v[64:67]
	v_mfma_f32_16x16x32_bf16 v[60:63], v[184:187], v[228:231], v[60:63]
	v_mfma_f32_16x16x32_bf16 v[60:63], v[208:211], v[232:235], v[60:63]
	v_mfma_f32_16x16x32_bf16 v[96:99], v[176:179], v[236:239], v[96:99]
	v_mfma_f32_16x16x32_bf16 v[96:99], v[180:183], v[240:243], v[96:99]
	s_setprio 2
	s_barrier
	v_mfma_f32_16x16x32_bf16 v[92:95], v[184:187], v[236:239], v[92:95]
	v_mfma_f32_16x16x32_bf16 v[92:95], v[208:211], v[240:243], v[92:95]
	s_setprio 0
	s_add_i32 s10, s25, s66
	v_lshl_add_u64 v[160:161], s[62:63], 0, v[2:3]
	s_mov_b32 m0, s10
	ds_read_b128 v[212:215], v197 offset:16384
	ds_read_b128 v[216:219], v197 offset:17408
	ds_read_b128 v[220:223], v197 offset:18432
	ds_read_b128 v[224:227], v197 offset:19456
	ds_read_b128 v[228:231], v197 offset:20480
	ds_read_b128 v[232:235], v197 offset:21504
	ds_read_b128 v[236:239], v197 offset:22528
	ds_read_b128 v[240:243], v197 offset:23552
	global_load_lds_dwordx4 v[160:161], off
	s_add_i32 m0, s10, 0x2000
	s_add_u32 s10, s62, 0x160000
	v_lshl_add_u64 v[162:163], s[62:63], 0, v[150:151]
	s_addc_u32 s11, s63, 0
	s_add_i32 s19, s19, s66
	global_load_lds_dwordx4 v[162:163], off
	v_lshl_add_u64 v[244:245], s[10:11], 0, v[2:3]
	s_mov_b32 m0, s19
	v_lshl_add_u64 v[246:247], s[64:65], 0, v[148:149]
	global_load_lds_dwordx4 v[244:245], off
	v_lshl_add_u64 v[244:245], s[10:11], 0, v[150:151]
	s_add_i32 m0, s19, 0x2000
	s_nop 0
	global_load_lds_dwordx4 v[244:245], off
	v_lshl_add_u64 v[244:245], s[64:65], 0, v[0:1]
	s_mov_b32 m0, s67
	s_nop 0
	global_load_lds_dwordx4 v[244:245], off
	s_mov_b32 m0, s75
	s_nop 0
	global_load_lds_dwordx4 v[246:247], off
	s_waitcnt vmcnt(8)
	s_waitcnt lgkmcnt(0)
	s_barrier
	s_setprio 1
	s_waitcnt lgkmcnt(0)
	v_mfma_f32_16x16x32_bf16 v[128:131], v[136:139], v[212:215], v[128:131]
	v_mfma_f32_16x16x32_bf16 v[128:131], v[140:143], v[216:219], v[128:131]
	v_mfma_f32_16x16x32_bf16 v[124:127], v[144:147], v[212:215], v[124:127]
	v_mfma_f32_16x16x32_bf16 v[124:127], v[172:175], v[216:219], v[124:127]
	v_mfma_f32_16x16x32_bf16 v[104:107], v[136:139], v[220:223], v[104:107]
	v_mfma_f32_16x16x32_bf16 v[104:107], v[140:143], v[224:227], v[104:107]
	v_mfma_f32_16x16x32_bf16 v[100:103], v[144:147], v[220:223], v[100:103]
	v_mfma_f32_16x16x32_bf16 v[100:103], v[172:175], v[224:227], v[100:103]
	v_mfma_f32_16x16x32_bf16 v[72:75], v[136:139], v[228:231], v[72:75]
	v_mfma_f32_16x16x32_bf16 v[72:75], v[140:143], v[232:235], v[72:75]
	v_mfma_f32_16x16x32_bf16 v[68:71], v[144:147], v[228:231], v[68:71]
	v_mfma_f32_16x16x32_bf16 v[68:71], v[172:175], v[232:235], v[68:71]
	v_mfma_f32_16x16x32_bf16 v[32:35], v[136:139], v[236:239], v[32:35]
	v_mfma_f32_16x16x32_bf16 v[32:35], v[140:143], v[240:243], v[32:35]
	v_mfma_f32_16x16x32_bf16 v[28:31], v[144:147], v[236:239], v[28:31]
	v_mfma_f32_16x16x32_bf16 v[28:31], v[172:175], v[240:243], v[28:31]
	s_setprio 0
	s_setprio 1
	v_mfma_f32_16x16x32_bf16 v[120:123], v[176:179], v[212:215], v[120:123]
	v_mfma_f32_16x16x32_bf16 v[120:123], v[180:183], v[216:219], v[120:123]
	v_mfma_f32_16x16x32_bf16 v[116:119], v[184:187], v[212:215], v[116:119]
	v_mfma_f32_16x16x32_bf16 v[116:119], v[208:211], v[216:219], v[116:119]
	v_mfma_f32_16x16x32_bf16 v[84:87], v[176:179], v[220:223], v[84:87]
	v_mfma_f32_16x16x32_bf16 v[84:87], v[180:183], v[224:227], v[84:87]
	v_mfma_f32_16x16x32_bf16 v[80:83], v[184:187], v[220:223], v[80:83]
	v_mfma_f32_16x16x32_bf16 v[80:83], v[208:211], v[224:227], v[80:83]
	v_mfma_f32_16x16x32_bf16 v[48:51], v[176:179], v[228:231], v[48:51]
	v_mfma_f32_16x16x32_bf16 v[48:51], v[180:183], v[232:235], v[48:51]
	v_mfma_f32_16x16x32_bf16 v[44:47], v[184:187], v[228:231], v[44:47]
	v_mfma_f32_16x16x32_bf16 v[44:47], v[208:211], v[232:235], v[44:47]
	v_mfma_f32_16x16x32_bf16 v[24:27], v[176:179], v[236:239], v[24:27]
	v_mfma_f32_16x16x32_bf16 v[24:27], v[180:183], v[240:243], v[24:27]
	s_setprio 2
	s_barrier
; #define PG8_STAGE(bufoff, gbase, voff) do { _Pragma("unroll") for (int _i = 0; _i < 2; ++_i) \
;         __builtin_amdgcn_global_load_lds((const unsigned*)((const char*)(gbase) + (voff)[_i]), (LAS unsigned*)(lds + (bufoff) + ldsw + _i * 8192), 16, 0, 0); } while (0)
; #define PG8_LDA(dst, b, h) do { _Pragma("unroll") for (int m = 0; m < 4; ++m) _Pragma("unroll") for (int k = 0; k < 2; ++k) dst[m][k] = *(const LAS bf16x8*)(lds + PG8_SA(b, h) + aoff + m * 2048 + k * 1024); } while (0)
; #define PG8_LDB(dst, b, h) do { _Pragma("unroll") for (int n = 0; n < 2; ++n) _Pragma("unroll") for (int k = 0; k < 2; ++k) dst[n][k] = *(const LAS bf16x8*)(lds + PG8_SB(b, h) + boff + n * 2048 + k * 1024); } while (0)
; #define PG8_MMA(ai, bj, At, Bt) do { __builtin_amdgcn_s_setprio(1); _Pragma("unroll") for (int m = 0; m < 4; ++m) _Pragma("unroll") for (int n = 0; n < 2; ++n) _Pragma("unroll") for (int k = 0; k < 2; ++k) \
;         acc[ai][bj][m][n] = __builtin_amdgcn_mfma_f32_16x16x32_bf16(Bt[n][k], At[m][k], acc[ai][bj][m][n], 0, 0, 0); __builtin_amdgcn_s_setprio(0); } while (0)
; #define PG8_WAIT_V(n) asm volatile("s_waitcnt vmcnt(" #n ")" ::: "memory")
; #define PG8_WAIT_L(n) asm volatile("s_waitcnt lgkmcnt(" #n ")" ::: "memory")
; #define PG8_BAR __builtin_amdgcn_s_barrier()
; #define PG8_SCHED __builtin_amdgcn_sched_barrier(0)
; template <class Epi, class Sched, bool ALIGN_EPI = true>
; __device__ __forceinline__ void gemm_phase(LAS unsigned char* lds, const Gemm g, const Sched& S, const Epi& E) {
;     ...
;             PG8_WAIT_V(8); PG8_WAIT_L(0); PG8_BAR; PG8_MMA(1, 0, At, B0); PG8_MMA(1, 1, At, B1); PG8_BAR; PG8_SCHED;
;             PG8_LDB(B0, 1, 0); PG8_LDB(B1, 1, 1); PG8_SCHED; PG8_LDA(At, 1, 0); PG8_STAGE(PG8_SA(0, 1), a2 + hA, voffA);
;             PG8_WAIT_V(8); PG8_WAIT_L(0); PG8_BAR; PG8_MMA(0, 0, At, B0); PG8_MMA(0, 1, At, B1); PG8_BAR; PG8_SCHED;
	v_mfma_f32_16x16x32_bf16 v[20:23], v[184:187], v[236:239], v[20:23]
	v_mfma_f32_16x16x32_bf16 v[20:23], v[208:211], v[240:243], v[20:23]
	s_setprio 0
	s_add_i32 s19, 0, 0x18000
	s_add_i32 s24, 0, 0x1c000
	v_add_u32_e32 v172, s19, v188
	v_add_u32_e32 v207, s24, v188
	ds_read_b128 v[136:139], v172
	ds_read_b128 v[140:143], v172 offset:1024
	ds_read_b128 v[144:147], v172 offset:2048
	ds_read_b128 v[172:175], v172 offset:3072
	ds_read_b128 v[176:179], v207
	ds_read_b128 v[180:183], v207 offset:1024
	ds_read_b128 v[184:187], v207 offset:2048
	ds_read_b128 v[208:211], v207 offset:3072
	s_add_u32 s10, s64, 0x160000
	s_addc_u32 s11, s65, 0
	s_mov_b32 m0, s76
	v_lshl_add_u64 v[248:249], s[10:11], 0, v[0:1]
	ds_read_b128 v[212:215], v197 offset:32768
	ds_read_b128 v[216:219], v197 offset:33792
	ds_read_b128 v[220:223], v197 offset:34816
	ds_read_b128 v[224:227], v197 offset:35840
	ds_read_b128 v[228:231], v197 offset:36864
	ds_read_b128 v[232:235], v197 offset:37888
	ds_read_b128 v[236:239], v197 offset:38912
	ds_read_b128 v[240:243], v197 offset:39936
	global_load_lds_dwordx4 v[248:249], off
	v_lshl_add_u64 v[248:249], s[10:11], 0, v[148:149]
	s_mov_b32 m0, s77
	s_nop 0
	global_load_lds_dwordx4 v[248:249], off
	s_waitcnt vmcnt(8)
	s_waitcnt lgkmcnt(0)
	s_barrier
	s_setprio 1
	s_waitcnt lgkmcnt(0)
	v_mfma_f32_16x16x32_bf16 v[16:19], v[136:139], v[212:215], v[16:19]
	v_mfma_f32_16x16x32_bf16 v[16:19], v[140:143], v[216:219], v[16:19]
	v_mfma_f32_16x16x32_bf16 v[12:15], v[144:147], v[212:215], v[12:15]
	v_mfma_f32_16x16x32_bf16 v[12:15], v[172:175], v[216:219], v[12:15]
	v_mfma_f32_16x16x32_bf16 v[56:59], v[136:139], v[220:223], v[56:59]
	v_mfma_f32_16x16x32_bf16 v[56:59], v[140:143], v[224:227], v[56:59]
	v_mfma_f32_16x16x32_bf16 v[52:55], v[144:147], v[220:223], v[52:55]
	v_mfma_f32_16x16x32_bf16 v[52:55], v[172:175], v[224:227], v[52:55]
	v_mfma_f32_16x16x32_bf16 v[88:91], v[136:139], v[228:231], v[88:91]
	v_mfma_f32_16x16x32_bf16 v[88:91], v[140:143], v[232:235], v[88:91]
	v_mfma_f32_16x16x32_bf16 v[76:79], v[144:147], v[228:231], v[76:79]
	v_mfma_f32_16x16x32_bf16 v[76:79], v[172:175], v[232:235], v[76:79]
	v_mfma_f32_16x16x32_bf16 v[112:115], v[136:139], v[236:239], v[112:115]
	v_mfma_f32_16x16x32_bf16 v[112:115], v[140:143], v[240:243], v[112:115]
	v_mfma_f32_16x16x32_bf16 v[108:111], v[144:147], v[236:239], v[108:111]
	v_mfma_f32_16x16x32_bf16 v[108:111], v[172:175], v[240:243], v[108:111]
	s_setprio 0
	s_setprio 1
	v_mfma_f32_16x16x32_bf16 v[8:11], v[176:179], v[212:215], v[8:11]
	v_mfma_f32_16x16x32_bf16 v[8:11], v[180:183], v[216:219], v[8:11]
	v_mfma_f32_16x16x32_bf16 v[4:7], v[184:187], v[212:215], v[4:7]
	v_mfma_f32_16x16x32_bf16 v[4:7], v[208:211], v[216:219], v[4:7]
	v_mfma_f32_16x16x32_bf16 v[40:43], v[176:179], v[220:223], v[40:43]
	v_mfma_f32_16x16x32_bf16 v[40:43], v[180:183], v[224:227], v[40:43]
	v_mfma_f32_16x16x32_bf16 v[36:39], v[184:187], v[220:223], v[36:39]
	v_mfma_f32_16x16x32_bf16 v[36:39], v[208:211], v[224:227], v[36:39]
	v_mfma_f32_16x16x32_bf16 v[64:67], v[176:179], v[228:231], v[64:67]
	v_mfma_f32_16x16x32_bf16 v[64:67], v[180:183], v[232:235], v[64:67]
	v_mfma_f32_16x16x32_bf16 v[60:63], v[184:187], v[228:231], v[60:63]
	v_mfma_f32_16x16x32_bf16 v[60:63], v[208:211], v[232:235], v[60:63]
	v_mfma_f32_16x16x32_bf16 v[96:99], v[176:179], v[236:239], v[96:99]
	v_mfma_f32_16x16x32_bf16 v[96:99], v[180:183], v[240:243], v[96:99]
	s_setprio 2
	s_barrier
; #define PG8_STAGE(bufoff, gbase, voff) do { _Pragma("unroll") for (int _i = 0; _i < 2; ++_i) \
;         __builtin_amdgcn_global_load_lds((const unsigned*)((const char*)(gbase) + (voff)[_i]), (LAS unsigned*)(lds + (bufoff) + ldsw + _i * 8192), 16, 0, 0); } while (0)
; #define PG8_LDA(dst, b, h) do { _Pragma("unroll") for (int m = 0; m < 4; ++m) _Pragma("unroll") for (int k = 0; k < 2; ++k) dst[m][k] = *(const LAS bf16x8*)(lds + PG8_SA(b, h) + aoff + m * 2048 + k * 1024); } while (0)
; #define PG8_MMA(ai, bj, At, Bt) do { __builtin_amdgcn_s_setprio(1); _Pragma("unroll") for (int m = 0; m < 4; ++m) _Pragma("unroll") for (int n = 0; n < 2; ++n) _Pragma("unroll") for (int k = 0; k < 2; ++k) \
;         acc[ai][bj][m][n] = __builtin_amdgcn_mfma_f32_16x16x32_bf16(Bt[n][k], At[m][k], acc[ai][bj][m][n], 0, 0, 0); __builtin_amdgcn_s_setprio(0); } while (0)
; #define PG8_WAIT_V(n) asm volatile("s_waitcnt vmcnt(" #n ")" ::: "memory")
; #define PG8_WAIT_L(n) asm volatile("s_waitcnt lgkmcnt(" #n ")" ::: "memory")
; #define PG8_BAR __builtin_amdgcn_s_barrier()
; #define PG8_SCHED __builtin_amdgcn_sched_barrier(0)
; template <class Epi, class Sched, bool ALIGN_EPI = true>
; __device__ __forceinline__ void gemm_phase(LAS unsigned char* lds, const Gemm g, const Sched& S, const Epi& E) {
;     ...
;             const bool last = (t == nt - 2);
;             const char* a1 = cA + (size_t)(t + 1) * kstep;
;             const char* a2 = last ? nA : cA + (size_t)(t + 2) * kstep; const char* b2 = last ? nB : cB + (size_t)(t + 2) * kstep;
;             const char* a3 = a2 + kstep; const char* b3 = b2 + kstep;
;     ...
;             PG8_WAIT_V(8); PG8_WAIT_L(0); PG8_BAR; PG8_MMA(0, 0, At, B0); PG8_MMA(0, 1, At, B1); PG8_BAR; PG8_SCHED;
;             PG8_LDA(At, 1, 1); PG8_STAGE(PG8_SB(1, 0), b3, voffB); PG8_STAGE(PG8_SB(1, 1), b3 + hB, voffB); PG8_STAGE(PG8_SA(1, 0), a3, voffA);
;             PG8_WAIT_V(8); PG8_WAIT_L(0); PG8_BAR; PG8_MMA(1, 0, At, B0); PG8_MMA(1, 1, At, B1); PG8_BAR; PG8_SCHED;
	v_mfma_f32_16x16x32_bf16 v[92:95], v[184:187], v[236:239], v[92:95]
	v_mfma_f32_16x16x32_bf16 v[92:95], v[208:211], v[240:243], v[92:95]
	s_setprio 0
	s_add_i32 s10, s19, s66
	v_lshl_add_u64 v[160:161], v[160:161], 0, s[86:87]
	s_mov_b32 m0, s10
	ds_read_b128 v[212:215], v197 offset:49152
	ds_read_b128 v[216:219], v197 offset:50176
	ds_read_b128 v[220:223], v197 offset:51200
	ds_read_b128 v[224:227], v197 offset:52224
	ds_read_b128 v[228:231], v197 offset:53248
	ds_read_b128 v[232:235], v197 offset:54272
	ds_read_b128 v[236:239], v197 offset:55296
	ds_read_b128 v[240:243], v197 offset:56320
	global_load_lds_dwordx4 v[160:161], off
	s_add_i32 m0, s10, 0x2000
	s_add_u32 s10, s62, 0x160080
	v_lshl_add_u64 v[160:161], v[162:163], 0, s[86:87]
	s_addc_u32 s11, s63, 0
	s_add_i32 s19, s24, s66
	global_load_lds_dwordx4 v[160:161], off
	v_lshl_add_u64 v[160:161], s[10:11], 0, v[2:3]
	s_mov_b32 m0, s19
	s_nop 0
	global_load_lds_dwordx4 v[160:161], off
	v_lshl_add_u64 v[160:161], s[10:11], 0, v[150:151]
	s_add_i32 m0, s19, 0x2000
	s_nop 0
	global_load_lds_dwordx4 v[160:161], off
	v_lshl_add_u64 v[160:161], v[244:245], 0, s[86:87]
	s_mov_b32 m0, s80
	s_nop 0
	global_load_lds_dwordx4 v[160:161], off
	v_lshl_add_u64 v[160:161], v[246:247], 0, s[86:87]
	s_mov_b32 m0, s81
	s_nop 0
	global_load_lds_dwordx4 v[160:161], off
	s_waitcnt vmcnt(8)
	s_waitcnt lgkmcnt(0)
	s_barrier
	s_setprio 1
	s_waitcnt lgkmcnt(0)
	v_mfma_f32_16x16x32_bf16 v[128:131], v[136:139], v[212:215], v[128:131]
	v_mfma_f32_16x16x32_bf16 v[128:131], v[140:143], v[216:219], v[128:131]
	s_add_i32 s18, s18, 2
	s_mov_b64 s[10:11], vcc
	s_add_u32 vcc_lo, s10, 0x100
	v_mfma_f32_16x16x32_bf16 v[124:127], v[144:147], v[212:215], v[124:127]
	v_mfma_f32_16x16x32_bf16 v[124:127], v[172:175], v[216:219], v[124:127]
	s_addc_u32 vcc_hi, s11, 0
	s_add_u32 s19, s16, s10
	v_mfma_f32_16x16x32_bf16 v[104:107], v[136:139], v[220:223], v[104:107]
	v_mfma_f32_16x16x32_bf16 v[104:107], v[140:143], v[224:227], v[104:107]
	s_addc_u32 s24, s17, s11
	s_add_i32 s25, 0, 0x10000
	v_mfma_f32_16x16x32_bf16 v[100:103], v[144:147], v[220:223], v[100:103]
	v_mfma_f32_16x16x32_bf16 v[100:103], v[172:175], v[224:227], v[100:103]
	s_cmpk_eq_i32 s18, 0x54
	s_cselect_b32 s65, s61, s24
	v_mfma_f32_16x16x32_bf16 v[72:75], v[136:139], v[228:231], v[72:75]
	v_mfma_f32_16x16x32_bf16 v[72:75], v[140:143], v[232:235], v[72:75]
	s_cselect_b32 s24, 0, vcc_lo
	s_cselect_b32 s64, s60, s19
	v_mfma_f32_16x16x32_bf16 v[68:71], v[144:147], v[228:231], v[68:71]
	v_mfma_f32_16x16x32_bf16 v[68:71], v[172:175], v[232:235], v[68:71]
	s_cselect_b32 s19, 0, vcc_hi
	s_add_u32 s62, s2, s24
	v_mfma_f32_16x16x32_bf16 v[32:35], v[136:139], v[236:239], v[32:35]
	v_mfma_f32_16x16x32_bf16 v[32:35], v[140:143], v[240:243], v[32:35]
	s_addc_u32 s63, s3, s19
	s_add_i32 s19, 0, 0x14000
	v_mfma_f32_16x16x32_bf16 v[28:31], v[144:147], v[236:239], v[28:31]
	v_mfma_f32_16x16x32_bf16 v[28:31], v[172:175], v[240:243], v[28:31]
	s_setprio 0
	s_setprio 1
	v_mfma_f32_16x16x32_bf16 v[120:123], v[176:179], v[212:215], v[120:123]
	v_mfma_f32_16x16x32_bf16 v[120:123], v[180:183], v[216:219], v[120:123]
	v_mfma_f32_16x16x32_bf16 v[116:119], v[184:187], v[212:215], v[116:119]
	v_mfma_f32_16x16x32_bf16 v[116:119], v[208:211], v[216:219], v[116:119]
	v_mfma_f32_16x16x32_bf16 v[84:87], v[176:179], v[220:223], v[84:87]
	v_mfma_f32_16x16x32_bf16 v[84:87], v[180:183], v[224:227], v[84:87]
	v_mfma_f32_16x16x32_bf16 v[80:83], v[184:187], v[220:223], v[80:83]
	v_mfma_f32_16x16x32_bf16 v[80:83], v[208:211], v[224:227], v[80:83]
	v_mfma_f32_16x16x32_bf16 v[48:51], v[176:179], v[228:231], v[48:51]
	v_mfma_f32_16x16x32_bf16 v[48:51], v[180:183], v[232:235], v[48:51]
	v_mfma_f32_16x16x32_bf16 v[44:47], v[184:187], v[228:231], v[44:47]
	v_mfma_f32_16x16x32_bf16 v[44:47], v[208:211], v[232:235], v[44:47]
	v_mfma_f32_16x16x32_bf16 v[24:27], v[176:179], v[236:239], v[24:27]
	v_mfma_f32_16x16x32_bf16 v[24:27], v[180:183], v[240:243], v[24:27]
	s_setprio 2
	s_barrier
	v_mfma_f32_16x16x32_bf16 v[20:23], v[184:187], v[236:239], v[20:23]
	v_mfma_f32_16x16x32_bf16 v[20:23], v[208:211], v[240:243], v[20:23]
	s_setprio 0
	s_cmpk_gt_u32 s18, 0x55
	s_cbranch_scc0 .LBB0_1111
